# gate tiles (GEMM1 writer + up GEMM readers) use bit-scattered row-major-like layout instead of 1KB-contiguous per wave-instr
# speedup vs baseline: 1.0126x; 1.0126x over previous
; __device__ __forceinline__ float bf_lo(unsigned w) { return __uint_as_float(w << 16); }
; __device__ __forceinline__ float bf_hi(unsigned w) { return __uint_as_float(w & 0xffff0000u); }
; #define EPI_LANE() int t__ = threadIdx.x; asm volatile("" : "+v"(t__)); const int wid__ = __builtin_amdgcn_readfirstlane(t__ >> 6); wr = wid__ >> 2; wc = wid__ & 3; fr = t__ & 15; fq = (t__ & 63) >> 4
;     __device__ __forceinline__ const char* gbase(int br, const Unit& u, int wid) const { return (const char*)G + ((size_t)(((br * 4 + u.pn) * 128 + u.pm) * 8 + wid)) * 16384; }
; #define RT(a, b) ((b) * __builtin_amdgcn_rcpf(a))
;     __device__ __forceinline__ void hook(f32x4 (&acc)[2][2][4][2], const Unit& u, int which, int wr, int wc, int fr, int fq) const {
;         EPI_LANE();
;         const char* gn_b = gbase(which, u, wid__); const char* gd_b = gbase(which + 1, u, wid__);
;         unsigned off0 = (unsigned)((t__ & 63) * 16); asm volatile("" : "+v"(off0));
; #pragma unroll
;         for (int ai = 0; ai < 2; ++ai) {
;                 u32x4 gnv[4][2], gdv[4][2];
; #pragma unroll
;                 for (int m = 0; m < 4; ++m)
; #pragma unroll
;                     for (int bj = 0; bj < 2; ++bj) { const unsigned off = off0 + (unsigned)(((ai * 4 + m) * 2 + bj) * 1024);
;                         gnv[m][bj] = *(const u32x4*)(gn_b + off); gdv[m][bj] = *(const u32x4*)(gd_b + off); }
; #pragma unroll
;                 for (int m = 0; m < 4; ++m)
; #pragma unroll
;                     for (int bj = 0; bj < 2; ++bj) { const u32x4 gn = gnv[m][bj], gd = gdv[m][bj];
;     ...
;                         f32x4 r0, r1;
;                         r0[0] = RT(bf_lo(gn.x), bf_lo(gd.x)); r0[1] = RT(bf_hi(gn.x), bf_hi(gd.x)); r0[2] = RT(bf_lo(gn.y), bf_lo(gd.y)); r0[3] = RT(bf_hi(gn.y), bf_hi(gd.y));
;                         r1[0] = RT(bf_lo(gn.z), bf_lo(gd.z)); r1[1] = RT(bf_hi(gn.z), bf_hi(gd.z)); r1[2] = RT(bf_lo(gn.w), bf_lo(gd.w)); r1[3] = RT(bf_hi(gn.w), bf_hi(gd.w));
;     ...
;                         acc[ai][bj][m][0] *= r0; acc[ai][bj][m][1] *= r1; }
;                 asm volatile("" : "+v"(off0) :: "memory"); }
.LBB0_52:
	s_andn2_b64 vcc, exec, s[66:67]
	s_cbranch_vccnz .LBB0_54
	v_mov_b32_e32 v96, v212
	s_nop 0
	v_readfirstlane_b32 s66, v96
	s_mov_b32 s66, 0
	s_cmp_eq_u32 s86, 4
	s_cselect_b32 s67, 0, 0x1000
	s_add_i32 s66, s66, s36
	s_add_i32 s67, s67, s31
	s_add_i32 s68, s67, s66
	s_ashr_i32 s69, s68, 31
	s_lshl_b64 s[66:67], s[68:69], 14
	s_add_u32 s66, s33, s66
	s_addc_u32 s67, s37, s67
	s_addk_i32 s68, 0x1000
	s_ashr_i32 s69, s68, 31
	v_lshlrev_b32_e32 v96, 4, v96
	s_lshl_b64 s[68:69], s[68:69], 14
	v_and_b32_e32 v96, 0x3f0, v96
	v_and_b32_e32 v98, 15, v212
	v_lshlrev_b32_e32 v98, 9, v98
	v_and_b32_e32 v99, 0xf0, v212
	v_or_b32_e32 v98, v98, v99
	v_and_b32_e32 v99, 0x100, v212
	v_lshlrev_b32_e32 v99, 7, v99
	v_or_b32_e32 v96, v98, v99
	s_add_u32 s68, s33, s68
	s_addc_u32 s69, s37, s69
	global_load_dwordx4 v[232:235], v96, s[66:67]
	global_load_dwordx4 v[236:239], v96, s[68:69]
	v_add_u32_e32 v98, 0x100, v96
	global_load_dwordx4 v[184:187], v98, s[66:67]
	global_load_dwordx4 v[180:183], v98, s[68:69]
	v_add_u32_e32 v98, 0x2000, v96
	global_load_dwordx4 v[176:179], v98, s[66:67]
	global_load_dwordx4 v[172:175], v98, s[68:69]
	v_add_u32_e32 v98, 0x2100, v96
	global_load_dwordx4 v[168:171], v98, s[66:67]
	global_load_dwordx4 v[164:167], v98, s[68:69]
	v_add_u32_e32 v98, 0x4000, v96
	global_load_dwordx4 v[160:163], v98, s[66:67]
	global_load_dwordx4 v[156:159], v98, s[68:69]
	v_add_u32_e32 v98, 0x4100, v96
	global_load_dwordx4 v[152:155], v98, s[66:67]
	global_load_dwordx4 v[148:151], v98, s[68:69]
	v_add_u32_e32 v98, 0x6000, v96
	global_load_dwordx4 v[136:139], v98, s[66:67]
	global_load_dwordx4 v[132:135], v98, s[68:69]
	v_add_u32_e32 v98, 0x6100, v96
	global_load_dwordx4 v[140:143], v98, s[66:67]
	global_load_dwordx4 v[144:147], v98, s[68:69]
	s_waitcnt vmcnt(0)
	v_lshlrev_b32_e32 v231, 16, v233
	v_lshlrev_b32_e32 v98, 16, v232
	v_and_b32_e32 v99, 0xffff0000, v232
	v_rcp_f32_e32 v232, v231
	v_and_b32_e32 v231, 0xffff0000, v233
	v_rcp_f32_e32 v233, v231
	v_rcp_f32_e32 v98, v98
	v_rcp_f32_e32 v99, v99
	v_lshlrev_b32_e32 v240, 16, v236
	v_and_b32_e32 v241, 0xffff0000, v236
	v_lshlrev_b32_e32 v236, 16, v237
	v_and_b32_e32 v237, 0xffff0000, v237
	v_pk_mul_f32 v[232:233], v[232:233], v[236:237]
	v_pk_mul_f32 v[98:99], v[98:99], v[240:241]
	v_pk_mul_f32 v[130:131], v[130:131], v[232:233]
	v_lshlrev_b32_e32 v232, 16, v180
	v_and_b32_e32 v233, 0xffff0000, v180
	v_lshlrev_b32_e32 v180, 16, v185
	v_pk_mul_f32 v[128:129], v[128:129], v[98:99]
	v_lshlrev_b32_e32 v98, 16, v184
	v_and_b32_e32 v99, 0xffff0000, v184
	v_rcp_f32_e32 v184, v180
	v_and_b32_e32 v180, 0xffff0000, v185
	v_rcp_f32_e32 v185, v180
	v_rcp_f32_e32 v98, v98
	v_rcp_f32_e32 v99, v99
	v_lshlrev_b32_e32 v180, 16, v181
	v_and_b32_e32 v181, 0xffff0000, v181
	v_pk_mul_f32 v[180:181], v[184:185], v[180:181]
	v_pk_mul_f32 v[98:99], v[98:99], v[232:233]
	v_pk_mul_f32 v[126:127], v[126:127], v[180:181]
	v_lshlrev_b32_e32 v180, 16, v172
	v_and_b32_e32 v181, 0xffff0000, v172
	v_lshlrev_b32_e32 v172, 16, v177
	v_pk_mul_f32 v[124:125], v[124:125], v[98:99]
	v_lshlrev_b32_e32 v98, 16, v176
	v_and_b32_e32 v99, 0xffff0000, v176
	v_rcp_f32_e32 v176, v172
	v_and_b32_e32 v172, 0xffff0000, v177
	v_rcp_f32_e32 v98, v98
	v_rcp_f32_e32 v99, v99
	v_rcp_f32_e32 v177, v172
	v_lshlrev_b32_e32 v172, 16, v173
	v_and_b32_e32 v173, 0xffff0000, v173
	v_pk_mul_f32 v[98:99], v[98:99], v[180:181]
	v_pk_mul_f32 v[172:173], v[176:177], v[172:173]
	v_pk_mul_f32 v[112:113], v[112:113], v[98:99]
	v_pk_mul_f32 v[114:115], v[114:115], v[172:173]
	v_lshlrev_b32_e32 v98, 16, v168
	v_and_b32_e32 v99, 0xffff0000, v168
	v_lshlrev_b32_e32 v172, 16, v164
	v_and_b32_e32 v173, 0xffff0000, v164
	v_lshlrev_b32_e32 v164, 16, v169
	v_rcp_f32_e32 v98, v98
	v_rcp_f32_e32 v99, v99
	v_rcp_f32_e32 v168, v164
	v_and_b32_e32 v164, 0xffff0000, v169
	v_rcp_f32_e32 v169, v164
	v_pk_mul_f32 v[98:99], v[98:99], v[172:173]
	v_lshlrev_b32_e32 v164, 16, v165
	v_and_b32_e32 v165, 0xffff0000, v165
	v_pk_mul_f32 v[164:165], v[168:169], v[164:165]
	v_pk_mul_f32 v[104:105], v[104:105], v[98:99]
	v_lshlrev_b32_e32 v98, 16, v160
	v_and_b32_e32 v99, 0xffff0000, v160
	v_pk_mul_f32 v[106:107], v[106:107], v[164:165]
	v_rcp_f32_e32 v98, v98
	v_rcp_f32_e32 v99, v99
	v_lshlrev_b32_e32 v164, 16, v156
	v_and_b32_e32 v165, 0xffff0000, v156
	v_lshlrev_b32_e32 v156, 16, v161
	v_rcp_f32_e32 v160, v156
	v_and_b32_e32 v156, 0xffff0000, v161
	v_rcp_f32_e32 v161, v156
	v_pk_mul_f32 v[98:99], v[98:99], v[164:165]
	v_lshlrev_b32_e32 v156, 16, v157
	v_and_b32_e32 v157, 0xffff0000, v157
	v_pk_mul_f32 v[92:93], v[92:93], v[98:99]
	v_lshlrev_b32_e32 v98, 16, v152
	v_and_b32_e32 v99, 0xffff0000, v152
	v_pk_mul_f32 v[156:157], v[160:161], v[156:157]
	v_rcp_f32_e32 v98, v98
	v_rcp_f32_e32 v99, v99
	v_pk_mul_f32 v[94:95], v[94:95], v[156:157]
	v_lshlrev_b32_e32 v156, 16, v148
	v_and_b32_e32 v157, 0xffff0000, v148
	v_lshlrev_b32_e32 v148, 16, v153
	v_rcp_f32_e32 v152, v148
	v_and_b32_e32 v148, 0xffff0000, v153
	v_rcp_f32_e32 v153, v148
	v_pk_mul_f32 v[98:99], v[98:99], v[156:157]
	v_lshlrev_b32_e32 v148, 16, v149
	v_pk_mul_f32 v[84:85], v[84:85], v[98:99]
	v_lshlrev_b32_e32 v98, 16, v136
	v_and_b32_e32 v99, 0xffff0000, v136
	v_and_b32_e32 v149, 0xffff0000, v149
	v_rcp_f32_e32 v98, v98
	v_rcp_f32_e32 v99, v99
	v_pk_mul_f32 v[148:149], v[152:153], v[148:149]
	v_lshlrev_b32_e32 v176, 16, v178
	v_pk_mul_f32 v[86:87], v[86:87], v[148:149]
	v_lshlrev_b32_e32 v148, 16, v132
	v_and_b32_e32 v149, 0xffff0000, v132
	v_lshlrev_b32_e32 v132, 16, v137
	v_rcp_f32_e32 v136, v132
	v_and_b32_e32 v132, 0xffff0000, v137
	v_pk_mul_f32 v[98:99], v[98:99], v[148:149]
	v_rcp_f32_e32 v137, v132
; __device__ __forceinline__ float bf_lo(unsigned w) { return __uint_as_float(w << 16); }
; __device__ __forceinline__ float bf_hi(unsigned w) { return __uint_as_float(w & 0xffff0000u); }
; #define RT(a, b) ((b) * __builtin_amdgcn_rcpf(a))
;     __device__ __forceinline__ void hook(f32x4 (&acc)[2][2][4][2], const Unit& u, int which, int wr, int wc, int fr, int fq) const {
;     ...
;         for (int ai = 0; ai < 2; ++ai) {
;                 u32x4 gnv[4][2], gdv[4][2];
; #pragma unroll
;                 for (int m = 0; m < 4; ++m)
; #pragma unroll
;                     for (int bj = 0; bj < 2; ++bj) { const unsigned off = off0 + (unsigned)(((ai * 4 + m) * 2 + bj) * 1024);
;                         gnv[m][bj] = *(const u32x4*)(gn_b + off); gdv[m][bj] = *(const u32x4*)(gd_b + off); }
; #pragma unroll
;                 for (int m = 0; m < 4; ++m)
; #pragma unroll
;                     for (int bj = 0; bj < 2; ++bj) { const u32x4 gn = gnv[m][bj], gd = gdv[m][bj];
;     ...
;                         f32x4 r0, r1;
;                         r0[0] = RT(bf_lo(gn.x), bf_lo(gd.x)); r0[1] = RT(bf_hi(gn.x), bf_hi(gd.x)); r0[2] = RT(bf_lo(gn.y), bf_lo(gd.y)); r0[3] = RT(bf_hi(gn.y), bf_hi(gd.y));
;                         r1[0] = RT(bf_lo(gn.z), bf_lo(gd.z)); r1[1] = RT(bf_hi(gn.z), bf_hi(gd.z)); r1[2] = RT(bf_lo(gn.w), bf_lo(gd.w)); r1[3] = RT(bf_hi(gn.w), bf_hi(gd.w));
;     ...
;                         acc[ai][bj][m][0] *= r0; acc[ai][bj][m][1] *= r1; }
;                 asm volatile("" : "+v"(off0) :: "memory"); }
	v_pk_mul_f32 v[76:77], v[76:77], v[98:99]
	v_lshlrev_b32_e32 v98, 16, v140
	v_and_b32_e32 v99, 0xffff0000, v140
	v_and_b32_e32 v177, 0xffff0000, v178
	v_lshlrev_b32_e32 v180, 16, v174
	v_and_b32_e32 v181, 0xffff0000, v174
	v_lshlrev_b32_e32 v174, 16, v179
	v_lshlrev_b32_e32 v168, 16, v170
	v_and_b32_e32 v169, 0xffff0000, v170
	v_lshlrev_b32_e32 v172, 16, v166
	v_and_b32_e32 v173, 0xffff0000, v166
	v_lshlrev_b32_e32 v166, 16, v171
	v_rcp_f32_e32 v98, v98
	v_rcp_f32_e32 v99, v99
	v_rcp_f32_e32 v176, v176
	v_rcp_f32_e32 v177, v177
	v_rcp_f32_e32 v178, v174
	v_and_b32_e32 v174, 0xffff0000, v179
	v_rcp_f32_e32 v168, v168
	v_rcp_f32_e32 v169, v169
	v_rcp_f32_e32 v170, v166
	v_and_b32_e32 v166, 0xffff0000, v171
	v_lshlrev_b32_e32 v132, 16, v133
	v_and_b32_e32 v133, 0xffff0000, v133
	v_rcp_f32_e32 v179, v174
	v_rcp_f32_e32 v171, v166
	v_pk_mul_f32 v[132:133], v[136:137], v[132:133]
	v_lshlrev_b32_e32 v232, 16, v182
	v_pk_mul_f32 v[78:79], v[78:79], v[132:133]
	v_lshlrev_b32_e32 v132, 16, v144
	v_and_b32_e32 v133, 0xffff0000, v144
	v_pk_mul_f32 v[98:99], v[98:99], v[132:133]
	v_and_b32_e32 v233, 0xffff0000, v182
	v_lshlrev_b32_e32 v182, 16, v187
	v_pk_mul_f32 v[176:177], v[176:177], v[180:181]
	v_lshlrev_b32_e32 v174, 16, v175
	v_and_b32_e32 v175, 0xffff0000, v175
	v_pk_mul_f32 v[168:169], v[168:169], v[172:173]
	v_lshlrev_b32_e32 v166, 16, v167
	v_and_b32_e32 v167, 0xffff0000, v167
	v_pk_mul_f32 v[68:69], v[68:69], v[98:99]
	v_add_u32_e32 v98, 0x10000, v96
	v_lshlrev_b32_e32 v184, 16, v186
	v_and_b32_e32 v185, 0xffff0000, v186
	v_rcp_f32_e32 v186, v182
	v_and_b32_e32 v182, 0xffff0000, v187
	v_pk_mul_f32 v[174:175], v[178:179], v[174:175]
	v_pk_mul_f32 v[108:109], v[108:109], v[176:177]
	v_pk_mul_f32 v[166:167], v[170:171], v[166:167]
	v_pk_mul_f32 v[100:101], v[100:101], v[168:169]
	global_load_dwordx4 v[168:171], v98, s[66:67]
	global_load_dwordx4 v[176:179], v98, s[68:69]
	v_rcp_f32_e32 v184, v184
	v_rcp_f32_e32 v185, v185
	v_rcp_f32_e32 v187, v182
	v_lshlrev_b32_e32 v231, 16, v234
	v_lshlrev_b32_e32 v182, 16, v183
	v_and_b32_e32 v183, 0xffff0000, v183
	v_rcp_f32_e32 v236, v231
	v_and_b32_e32 v231, 0xffff0000, v234
	v_pk_mul_f32 v[184:185], v[184:185], v[232:233]
	v_pk_mul_f32 v[182:183], v[186:187], v[182:183]
	v_add_u32_e32 v98, 0x10100, v96
	v_rcp_f32_e32 v237, v231
	v_lshlrev_b32_e32 v231, 16, v235
	v_pk_mul_f32 v[118:119], v[118:119], v[182:183]
	v_pk_mul_f32 v[116:117], v[116:117], v[184:185]
	global_load_dwordx4 v[180:183], v98, s[66:67]
	global_load_dwordx4 v[184:187], v98, s[68:69]
	v_rcp_f32_e32 v234, v231
	v_and_b32_e32 v231, 0xffff0000, v235
	v_rcp_f32_e32 v235, v231
	v_lshlrev_b32_e32 v240, 16, v238
	v_and_b32_e32 v241, 0xffff0000, v238
	v_lshlrev_b32_e32 v238, 16, v239
	v_and_b32_e32 v239, 0xffff0000, v239
	v_pk_mul_f32 v[236:237], v[236:237], v[240:241]
	v_pk_mul_f32 v[234:235], v[234:235], v[238:239]
	v_add_u32_e32 v98, 0x12000, v96
	v_pk_mul_f32 v[122:123], v[122:123], v[234:235]
	v_pk_mul_f32 v[120:121], v[120:121], v[236:237]
	global_load_dwordx4 v[232:235], v98, s[66:67]
	global_load_dwordx4 v[236:239], v98, s[68:69]
	v_lshlrev_b32_e32 v160, 16, v162
	v_and_b32_e32 v161, 0xffff0000, v162
	v_rcp_f32_e32 v160, v160
	v_rcp_f32_e32 v161, v161
	v_lshlrev_b32_e32 v164, 16, v158
	v_and_b32_e32 v165, 0xffff0000, v158
	v_add_u32_e32 v98, 0x12100, v96
	v_pk_mul_f32 v[110:111], v[110:111], v[174:175]
	v_pk_mul_f32 v[102:103], v[102:103], v[166:167]
	v_pk_mul_f32 v[160:161], v[160:161], v[164:165]
	global_load_dwordx4 v[172:175], v98, s[66:67]
	global_load_dwordx4 v[164:167], v98, s[68:69]
	v_lshlrev_b32_e32 v158, 16, v163
	v_rcp_f32_e32 v162, v158
	v_and_b32_e32 v158, 0xffff0000, v163
	v_rcp_f32_e32 v163, v158
	v_lshlrev_b32_e32 v152, 16, v154
	v_and_b32_e32 v153, 0xffff0000, v154
	v_rcp_f32_e32 v152, v152
	v_rcp_f32_e32 v153, v153
	v_lshlrev_b32_e32 v158, 16, v159
	v_and_b32_e32 v159, 0xffff0000, v159
	v_pk_mul_f32 v[158:159], v[162:163], v[158:159]
	v_lshlrev_b32_e32 v156, 16, v150
	v_and_b32_e32 v157, 0xffff0000, v150
	v_add_u32_e32 v98, 0x14000, v96
	v_pk_mul_f32 v[90:91], v[90:91], v[158:159]
	v_pk_mul_f32 v[88:89], v[88:89], v[160:161]
	v_pk_mul_f32 v[152:153], v[152:153], v[156:157]
	v_lshlrev_b32_e32 v150, 16, v155
	global_load_dwordx4 v[160:163], v98, s[66:67]
	global_load_dwordx4 v[156:159], v98, s[68:69]
	v_rcp_f32_e32 v154, v150
	v_and_b32_e32 v150, 0xffff0000, v155
	v_lshlrev_b32_e32 v148, 16, v134
	v_and_b32_e32 v149, 0xffff0000, v134
	v_lshlrev_b32_e32 v134, 16, v139
	v_rcp_f32_e32 v155, v150
	v_lshlrev_b32_e32 v136, 16, v138
	v_and_b32_e32 v137, 0xffff0000, v138
	v_rcp_f32_e32 v138, v134
	v_and_b32_e32 v134, 0xffff0000, v139
	v_rcp_f32_e32 v136, v136
	v_rcp_f32_e32 v137, v137
	v_rcp_f32_e32 v139, v134
	v_lshlrev_b32_e32 v132, 16, v141
	v_and_b32_e32 v133, 0xffff0000, v141
	v_lshlrev_b32_e32 v150, 16, v151
	v_and_b32_e32 v151, 0xffff0000, v151
	v_rcp_f32_e32 v132, v132
	v_rcp_f32_e32 v133, v133
	v_pk_mul_f32 v[150:151], v[154:155], v[150:151]
	v_lshlrev_b32_e32 v134, 16, v135
	v_and_b32_e32 v135, 0xffff0000, v135
	v_add_u32_e32 v98, 0x14100, v96
	v_pk_mul_f32 v[82:83], v[82:83], v[150:151]
	v_pk_mul_f32 v[80:81], v[80:81], v[152:153]
	v_pk_mul_f32 v[136:137], v[136:137], v[148:149]
	v_pk_mul_f32 v[134:135], v[138:139], v[134:135]
	global_load_dwordx4 v[152:155], v98, s[66:67]
	global_load_dwordx4 v[148:151], v98, s[68:69]
	v_pk_mul_f32 v[74:75], v[74:75], v[134:135]
	v_lshlrev_b32_e32 v134, 16, v145
	v_and_b32_e32 v135, 0xffff0000, v145
	v_pk_mul_f32 v[132:133], v[132:133], v[134:135]
	v_lshlrev_b32_e32 v134, 16, v142
	v_and_b32_e32 v135, 0xffff0000, v142
	v_rcp_f32_e32 v134, v134
	v_rcp_f32_e32 v135, v135
	v_pk_mul_f32 v[72:73], v[72:73], v[136:137]
	v_lshlrev_b32_e32 v136, 16, v146
	v_and_b32_e32 v137, 0xffff0000, v146
	v_add_u32_e32 v98, 0x16000, v96
	v_pk_mul_f32 v[134:135], v[134:135], v[136:137]
	v_lshlrev_b32_e32 v136, 16, v143
	v_and_b32_e32 v137, 0xffff0000, v143
	v_lshlrev_b32_e32 v138, 16, v147
	v_and_b32_e32 v139, 0xffff0000, v147
	global_load_dwordx4 v[144:147], v98, s[66:67]
	global_load_dwordx4 v[140:143], v98, s[68:69]
	v_rcp_f32_e32 v136, v136
	v_rcp_f32_e32 v137, v137
	v_add_u32_e32 v98, 0x16100, v96
	v_pk_mul_f32 v[70:71], v[70:71], v[132:133]
	v_pk_mul_f32 v[64:65], v[64:65], v[134:135]
	v_pk_mul_f32 v[136:137], v[136:137], v[138:139]
	s_waitcnt vmcnt(0)
; __device__ __forceinline__ float bf_lo(unsigned w) { return __uint_as_float(w << 16); }
; __device__ __forceinline__ float bf_hi(unsigned w) { return __uint_as_float(w & 0xffff0000u); }
; #define RT(a, b) ((b) * __builtin_amdgcn_rcpf(a))
;     __device__ __forceinline__ void hook(f32x4 (&acc)[2][2][4][2], const Unit& u, int which, int wr, int wc, int fr, int fq) const {
;     ...
;                 for (int m = 0; m < 4; ++m)
; #pragma unroll
;                     for (int bj = 0; bj < 2; ++bj) { const u32x4 gn = gnv[m][bj], gd = gdv[m][bj];
;     ...
;                         f32x4 r0, r1;
;                         r0[0] = RT(bf_lo(gn.x), bf_lo(gd.x)); r0[1] = RT(bf_hi(gn.x), bf_hi(gd.x)); r0[2] = RT(bf_lo(gn.y), bf_lo(gd.y)); r0[3] = RT(bf_hi(gn.y), bf_hi(gd.y));
;                         r1[0] = RT(bf_lo(gn.z), bf_lo(gd.z)); r1[1] = RT(bf_hi(gn.z), bf_hi(gd.z)); r1[2] = RT(bf_lo(gn.w), bf_lo(gd.w)); r1[3] = RT(bf_hi(gn.w), bf_hi(gd.w));
;     ...
;                         acc[ai][bj][m][0] *= r0; acc[ai][bj][m][1] *= r1; }
	v_and_b32_e32 v99, 0xffff0000, v168
	v_pk_mul_f32 v[66:67], v[66:67], v[136:137]
	global_load_dwordx4 v[136:139], v98, s[66:67]
	global_load_dwordx4 v[132:135], v98, s[68:69]
	v_lshlrev_b32_e32 v98, 16, v168
	v_rcp_f32_e32 v98, v98
	v_rcp_f32_e32 v99, v99
	v_lshlrev_b32_e32 v168, 16, v169
	v_and_b32_e32 v169, 0xffff0000, v169
	v_lshlrev_b32_e32 v240, 16, v176
	v_and_b32_e32 v241, 0xffff0000, v176
	v_rcp_f32_e32 v168, v168
	v_rcp_f32_e32 v169, v169
	v_pk_mul_f32 v[98:99], v[98:99], v[240:241]
	v_lshlrev_b32_e32 v176, 16, v177
	v_pk_mul_f32 v[60:61], v[60:61], v[98:99]
	v_lshlrev_b32_e32 v98, 16, v180
	v_and_b32_e32 v99, 0xffff0000, v180
	v_and_b32_e32 v177, 0xffff0000, v177
	v_rcp_f32_e32 v98, v98
	v_rcp_f32_e32 v99, v99
	v_pk_mul_f32 v[168:169], v[168:169], v[176:177]
	v_lshlrev_b32_e32 v176, 16, v170
	v_and_b32_e32 v170, 0xffff0000, v170
	v_rcp_f32_e32 v177, v170
	v_lshlrev_b32_e32 v170, 16, v171
	v_and_b32_e32 v171, 0xffff0000, v171
	v_rcp_f32_e32 v170, v170
	v_rcp_f32_e32 v171, v171
	v_pk_mul_f32 v[62:63], v[62:63], v[168:169]
	v_lshlrev_b32_e32 v168, 16, v184
	v_and_b32_e32 v169, 0xffff0000, v184
	v_pk_mul_f32 v[98:99], v[98:99], v[168:169]
	v_lshlrev_b32_e32 v168, 16, v181
	v_and_b32_e32 v169, 0xffff0000, v181
	v_rcp_f32_e32 v168, v168
	v_rcp_f32_e32 v169, v169
	v_lshlrev_b32_e32 v240, 16, v178
	v_and_b32_e32 v241, 0xffff0000, v178
	v_lshlrev_b32_e32 v178, 16, v179
	v_and_b32_e32 v179, 0xffff0000, v179
	v_pk_mul_f32 v[52:53], v[52:53], v[98:99]
	v_lshlrev_b32_e32 v98, 16, v232
	v_and_b32_e32 v99, 0xffff0000, v232
	v_pk_mul_f32 v[170:171], v[170:171], v[178:179]
	v_rcp_f32_e32 v98, v98
	v_rcp_f32_e32 v99, v99
	v_rcp_f32_e32 v176, v176
	v_pk_mul_f32 v[58:59], v[58:59], v[170:171]
	v_lshlrev_b32_e32 v170, 16, v185
	v_and_b32_e32 v171, 0xffff0000, v185
	v_pk_mul_f32 v[168:169], v[168:169], v[170:171]
	v_lshlrev_b32_e32 v170, 16, v182
	v_and_b32_e32 v171, 0xffff0000, v182
	v_rcp_f32_e32 v170, v170
	v_rcp_f32_e32 v171, v171
	v_pk_mul_f32 v[54:55], v[54:55], v[168:169]
	v_lshlrev_b32_e32 v168, 16, v236
	v_and_b32_e32 v169, 0xffff0000, v236
	v_pk_mul_f32 v[98:99], v[98:99], v[168:169]
	v_lshlrev_b32_e32 v168, 16, v233
	v_and_b32_e32 v169, 0xffff0000, v233
	v_pk_mul_f32 v[176:177], v[176:177], v[240:241]
	v_rcp_f32_e32 v168, v168
	v_rcp_f32_e32 v169, v169
	v_pk_mul_f32 v[56:57], v[56:57], v[176:177]
	v_lshlrev_b32_e32 v176, 16, v186
	v_and_b32_e32 v177, 0xffff0000, v186
	v_pk_mul_f32 v[44:45], v[44:45], v[98:99]
	v_lshlrev_b32_e32 v98, 16, v172
	v_and_b32_e32 v99, 0xffff0000, v172
	v_pk_mul_f32 v[170:171], v[170:171], v[176:177]
	v_rcp_f32_e32 v98, v98
	v_rcp_f32_e32 v99, v99
	v_pk_mul_f32 v[48:49], v[48:49], v[170:171]
	v_lshlrev_b32_e32 v170, 16, v237
	v_and_b32_e32 v171, 0xffff0000, v237
	v_pk_mul_f32 v[168:169], v[168:169], v[170:171]
	v_lshlrev_b32_e32 v176, 16, v183
	v_pk_mul_f32 v[46:47], v[46:47], v[168:169]
	v_lshlrev_b32_e32 v168, 16, v164
	v_and_b32_e32 v169, 0xffff0000, v164
	v_lshlrev_b32_e32 v164, 16, v173
	v_pk_mul_f32 v[98:99], v[98:99], v[168:169]
	v_rcp_f32_e32 v168, v164
	v_and_b32_e32 v164, 0xffff0000, v173
	v_rcp_f32_e32 v169, v164
	v_lshlrev_b32_e32 v164, 16, v165
	v_and_b32_e32 v165, 0xffff0000, v165
	v_pk_mul_f32 v[36:37], v[36:37], v[98:99]
	v_pk_mul_f32 v[164:165], v[168:169], v[164:165]
	v_lshlrev_b32_e32 v98, 16, v160
	v_pk_mul_f32 v[38:39], v[38:39], v[164:165]
	v_lshlrev_b32_e32 v164, 16, v156
	v_and_b32_e32 v165, 0xffff0000, v156
	v_lshlrev_b32_e32 v156, 16, v161
	v_and_b32_e32 v99, 0xffff0000, v160
	v_rcp_f32_e32 v160, v156
	v_and_b32_e32 v156, 0xffff0000, v161
	v_rcp_f32_e32 v161, v156
	v_rcp_f32_e32 v98, v98
	v_rcp_f32_e32 v99, v99
	v_lshlrev_b32_e32 v156, 16, v157
	v_and_b32_e32 v157, 0xffff0000, v157
	v_pk_mul_f32 v[156:157], v[160:161], v[156:157]
	v_pk_mul_f32 v[98:99], v[98:99], v[164:165]
	v_pk_mul_f32 v[30:31], v[30:31], v[156:157]
	v_lshlrev_b32_e32 v156, 16, v148
	v_and_b32_e32 v157, 0xffff0000, v148
	v_lshlrev_b32_e32 v148, 16, v153
	v_pk_mul_f32 v[28:29], v[28:29], v[98:99]
	v_lshlrev_b32_e32 v98, 16, v152
	v_and_b32_e32 v99, 0xffff0000, v152
	v_rcp_f32_e32 v152, v148
	v_and_b32_e32 v148, 0xffff0000, v153
	v_rcp_f32_e32 v153, v148
	v_rcp_f32_e32 v98, v98
	v_rcp_f32_e32 v99, v99
	v_lshlrev_b32_e32 v148, 16, v149
	v_and_b32_e32 v149, 0xffff0000, v149
	v_pk_mul_f32 v[148:149], v[152:153], v[148:149]
	v_pk_mul_f32 v[98:99], v[98:99], v[156:157]
	v_pk_mul_f32 v[22:23], v[22:23], v[148:149]
	v_lshlrev_b32_e32 v148, 16, v140
	v_and_b32_e32 v149, 0xffff0000, v140
	v_lshlrev_b32_e32 v140, 16, v145
	v_pk_mul_f32 v[20:21], v[20:21], v[98:99]
	v_lshlrev_b32_e32 v98, 16, v144
	v_and_b32_e32 v99, 0xffff0000, v144
	v_rcp_f32_e32 v144, v140
	v_and_b32_e32 v140, 0xffff0000, v145
	v_rcp_f32_e32 v98, v98
	v_rcp_f32_e32 v99, v99
	v_rcp_f32_e32 v145, v140
	v_and_b32_e32 v177, 0xffff0000, v183
	v_rcp_f32_e32 v176, v176
	v_rcp_f32_e32 v177, v177
	v_lshlrev_b32_e32 v140, 16, v141
	v_and_b32_e32 v141, 0xffff0000, v141
	v_lshlrev_b32_e32 v170, 16, v234
	v_and_b32_e32 v171, 0xffff0000, v234
	v_pk_mul_f32 v[98:99], v[98:99], v[148:149]
	v_pk_mul_f32 v[140:141], v[144:145], v[140:141]
	v_rcp_f32_e32 v170, v170
	v_rcp_f32_e32 v171, v171
	v_pk_mul_f32 v[18:19], v[18:19], v[140:141]
	v_pk_mul_f32 v[16:17], v[16:17], v[98:99]
	s_waitcnt vmcnt(0)
; __device__ __forceinline__ float bf_lo(unsigned w) { return __uint_as_float(w << 16); }
; __device__ __forceinline__ float bf_hi(unsigned w) { return __uint_as_float(w & 0xffff0000u); }
; #define RT(a, b) ((b) * __builtin_amdgcn_rcpf(a))
;     __device__ __forceinline__ void hook(f32x4 (&acc)[2][2][4][2], const Unit& u, int which, int wr, int wc, int fr, int fq) const {
;     ...
;                 for (int m = 0; m < 4; ++m)
; #pragma unroll
;                     for (int bj = 0; bj < 2; ++bj) { const u32x4 gn = gnv[m][bj], gd = gdv[m][bj];
;     ...
;                         f32x4 r0, r1;
;                         r0[0] = RT(bf_lo(gn.x), bf_lo(gd.x)); r0[1] = RT(bf_hi(gn.x), bf_hi(gd.x)); r0[2] = RT(bf_lo(gn.y), bf_lo(gd.y)); r0[3] = RT(bf_hi(gn.y), bf_hi(gd.y));
;                         r1[0] = RT(bf_lo(gn.z), bf_lo(gd.z)); r1[1] = RT(bf_hi(gn.z), bf_hi(gd.z)); r1[2] = RT(bf_lo(gn.w), bf_lo(gd.w)); r1[3] = RT(bf_hi(gn.w), bf_hi(gd.w));
;     ...
;                         acc[ai][bj][m][0] *= r0; acc[ai][bj][m][1] *= r1; }
	v_lshlrev_b32_e32 v98, 16, v136
	v_and_b32_e32 v99, 0xffff0000, v136
	v_lshlrev_b32_e32 v140, 16, v132
	v_and_b32_e32 v141, 0xffff0000, v132
	v_lshlrev_b32_e32 v132, 16, v137
	v_lshlrev_b32_e32 v178, 16, v187
	v_and_b32_e32 v179, 0xffff0000, v187
	v_lshlrev_b32_e32 v168, 16, v174
	v_and_b32_e32 v169, 0xffff0000, v174
	v_rcp_f32_e32 v98, v98
	v_rcp_f32_e32 v99, v99
	v_rcp_f32_e32 v136, v132
	v_and_b32_e32 v132, 0xffff0000, v137
	v_pk_mul_f32 v[176:177], v[176:177], v[178:179]
	v_rcp_f32_e32 v168, v168
	v_rcp_f32_e32 v169, v169
	v_rcp_f32_e32 v137, v132
	v_pk_mul_f32 v[50:51], v[50:51], v[176:177]
	v_lshlrev_b32_e32 v176, 16, v238
	v_and_b32_e32 v177, 0xffff0000, v238
	v_pk_mul_f32 v[170:171], v[170:171], v[176:177]
	v_lshlrev_b32_e32 v164, 16, v158
	v_pk_mul_f32 v[40:41], v[40:41], v[170:171]
	v_lshlrev_b32_e32 v170, 16, v166
	v_and_b32_e32 v171, 0xffff0000, v166
	v_lshlrev_b32_e32 v166, 16, v175
	v_and_b32_e32 v165, 0xffff0000, v158
	v_lshlrev_b32_e32 v158, 16, v163
	v_lshlrev_b32_e32 v156, 16, v150
	v_and_b32_e32 v157, 0xffff0000, v150
	v_lshlrev_b32_e32 v150, 16, v155
	v_lshlrev_b32_e32 v148, 16, v142
	v_and_b32_e32 v149, 0xffff0000, v142
	v_lshlrev_b32_e32 v142, 16, v147
	v_pk_mul_f32 v[98:99], v[98:99], v[140:141]
	v_lshlrev_b32_e32 v132, 16, v133
	v_and_b32_e32 v133, 0xffff0000, v133
	v_lshlrev_b32_e32 v140, 16, v134
	v_and_b32_e32 v141, 0xffff0000, v134
	v_lshlrev_b32_e32 v134, 16, v139
	v_lshlrev_b32_e32 v176, 16, v235
	v_and_b32_e32 v177, 0xffff0000, v235
	v_pk_mul_f32 v[168:169], v[168:169], v[170:171]
	v_rcp_f32_e32 v170, v166
	v_and_b32_e32 v166, 0xffff0000, v175
	v_lshlrev_b32_e32 v160, 16, v162
	v_and_b32_e32 v161, 0xffff0000, v162
	v_rcp_f32_e32 v162, v158
	v_and_b32_e32 v158, 0xffff0000, v163
	v_lshlrev_b32_e32 v152, 16, v154
	v_and_b32_e32 v153, 0xffff0000, v154
	v_rcp_f32_e32 v154, v150
	v_and_b32_e32 v150, 0xffff0000, v155
	v_lshlrev_b32_e32 v144, 16, v146
	v_and_b32_e32 v145, 0xffff0000, v146
	v_rcp_f32_e32 v146, v142
	v_and_b32_e32 v142, 0xffff0000, v147
	v_pk_mul_f32 v[132:133], v[136:137], v[132:133]
	v_lshlrev_b32_e32 v136, 16, v138
	v_and_b32_e32 v137, 0xffff0000, v138
	v_rcp_f32_e32 v138, v134
	v_and_b32_e32 v134, 0xffff0000, v139
	v_rcp_f32_e32 v176, v176
	v_rcp_f32_e32 v177, v177
	v_rcp_f32_e32 v171, v166
	v_rcp_f32_e32 v160, v160
	v_rcp_f32_e32 v161, v161
	v_rcp_f32_e32 v163, v158
	v_rcp_f32_e32 v152, v152
	v_rcp_f32_e32 v153, v153
	v_rcp_f32_e32 v155, v150
	v_rcp_f32_e32 v144, v144
	v_rcp_f32_e32 v145, v145
	v_rcp_f32_e32 v147, v142
	v_rcp_f32_e32 v136, v136
	v_rcp_f32_e32 v137, v137
	v_rcp_f32_e32 v139, v134
	v_lshlrev_b32_e32 v178, 16, v239
	v_and_b32_e32 v179, 0xffff0000, v239
	v_lshlrev_b32_e32 v166, 16, v167
	v_and_b32_e32 v167, 0xffff0000, v167
	v_lshlrev_b32_e32 v158, 16, v159
	v_and_b32_e32 v159, 0xffff0000, v159
	v_lshlrev_b32_e32 v150, 16, v151
	v_and_b32_e32 v151, 0xffff0000, v151
	v_lshlrev_b32_e32 v142, 16, v143
	v_and_b32_e32 v143, 0xffff0000, v143
	v_lshlrev_b32_e32 v134, 16, v135
	v_and_b32_e32 v135, 0xffff0000, v135
	v_pk_mul_f32 v[176:177], v[176:177], v[178:179]
	v_pk_mul_f32 v[166:167], v[170:171], v[166:167]
	v_pk_mul_f32 v[160:161], v[160:161], v[164:165]
	v_pk_mul_f32 v[158:159], v[162:163], v[158:159]
	v_pk_mul_f32 v[152:153], v[152:153], v[156:157]
	v_pk_mul_f32 v[150:151], v[154:155], v[150:151]
	v_pk_mul_f32 v[144:145], v[144:145], v[148:149]
	v_pk_mul_f32 v[142:143], v[146:147], v[142:143]
	v_pk_mul_f32 v[136:137], v[136:137], v[140:141]
	v_pk_mul_f32 v[134:135], v[138:139], v[134:135]
	v_pk_mul_f32 v[42:43], v[42:43], v[176:177]
	v_pk_mul_f32 v[34:35], v[34:35], v[166:167]
	v_pk_mul_f32 v[32:33], v[32:33], v[168:169]
	v_pk_mul_f32 v[26:27], v[26:27], v[158:159]
	v_pk_mul_f32 v[24:25], v[24:25], v[160:161]
	v_pk_mul_f32 v[14:15], v[14:15], v[150:151]
	v_pk_mul_f32 v[12:13], v[12:13], v[152:153]
	v_pk_mul_f32 v[10:11], v[10:11], v[142:143]
	v_pk_mul_f32 v[8:9], v[8:9], v[144:145]
	v_pk_mul_f32 v[6:7], v[6:7], v[132:133]
	v_pk_mul_f32 v[4:5], v[4:5], v[98:99]
	v_pk_mul_f32 v[2:3], v[2:3], v[134:135]
	v_pk_mul_f32 v[0:1], v[0:1], v[136:137]

; __device__ __forceinline__ float bf_lo(unsigned w) { return __uint_as_float(w << 16); }
; __device__ __forceinline__ float bf_hi(unsigned w) { return __uint_as_float(w & 0xffff0000u); }
; __device__ __forceinline__ unsigned cvt_pk_bf16(float lo, float hi) { f32x2_t v = {lo, hi}; bf16x2_t b = __builtin_convertvector(v, bf16x2_t); return __builtin_bit_cast(unsigned, b); }
; #define EPI_LANE() int t__ = threadIdx.x; asm volatile("" : "+v"(t__)); const int wid__ = __builtin_amdgcn_readfirstlane(t__ >> 6); wr = wid__ >> 2; wc = wid__ & 3; fr = t__ & 15; fq = (t__ & 63) >> 4
;     __device__ __forceinline__ void operator()(const f32x4 (&acc)[2][2][4][2], const Unit& u, int wr, int wc, int fr, int fq) const {
;         EPI_LANE();
;         const char* g_b = gbase(2, u, wid__) + (t__ & 63) * 16; char* mb = (char*)(Mg + (size_t)u.pm * BM * 1024 + u.pn * BM);
;         unsigned rl0 = (unsigned)(wr * 64 + fr), cl0 = (unsigned)(wc * 32 + 8 * fq); asm volatile("" : "+v"(rl0), "+v"(cl0));
; #pragma unroll
;         for (int ai = 0; ai < 2; ++ai) {
;             u32x4 gv[4][2];
; #pragma unroll
;             for (int m = 0; m < 4; ++m)
; #pragma unroll
;                 for (int bj = 0; bj < 2; ++bj) gv[m][bj] = *(const u32x4*)(g_b + ((ai * 4 + m) * 2 + bj) * 1024);
; #pragma unroll
;             for (int m = 0; m < 4; ++m) { const unsigned rl = rl0 + (unsigned)(ai * HALF + m * 16);
; #pragma unroll
;                 for (int bj = 0; bj < 2; ++bj) { const unsigned cl = cl0 + (unsigned)(bj * HALF);
;                     const u32x4 g = gv[m][bj];
;                     const f32x4 v0 = acc[ai][bj][m][0], v1 = acc[ai][bj][m][1];
;                     u32x4 w;
;                     w.x = cvt_pk_bf16(v0[0] * __builtin_amdgcn_rcpf(bf_lo(g.x)), v0[1] * __builtin_amdgcn_rcpf(bf_hi(g.x)));
;                     w.y = cvt_pk_bf16(v0[2] * __builtin_amdgcn_rcpf(bf_lo(g.y)), v0[3] * __builtin_amdgcn_rcpf(bf_hi(g.y)));
;                     w.z = cvt_pk_bf16(v1[0] * __builtin_amdgcn_rcpf(bf_lo(g.z)), v1[1] * __builtin_amdgcn_rcpf(bf_hi(g.z)));
;                     w.w = cvt_pk_bf16(v1[2] * __builtin_amdgcn_rcpf(bf_lo(g.w)), v1[3] * __builtin_amdgcn_rcpf(bf_hi(g.w)));
;                     *(u32x4*)(mb + (rl * 1024u + cl) * 2u) = w; } }
;             asm volatile("" : "+v"(rl0), "+v"(cl0) :: "memory"); }
.LBB0_57:
	v_mov_b32_e32 v132, v212
	s_lshl_b32 s61, s6, 10
	v_readfirstlane_b32 s31, v132
	s_lshl_b32 s62, s60, 3
	s_ashr_i32 s36, s31, 6
	s_add_i32 s61, s61, s62
	s_nop 0
	s_add_i32 s62, s61, 0x2000
	s_ashr_i32 s63, s62, 31
	s_lshl_b64 s[62:63], s[62:63], 14
	s_add_u32 s62, s33, s62
	s_addc_u32 s63, s37, s63
	s_ashr_i32 s61, s60, 31
	s_lshl_b64 s[60:61], s[60:61], 19
	s_add_u32 s64, s89, s60
	s_addc_u32 s65, s3, s61
	s_lshl_b32 s60, s6, 8
	s_ashr_i32 s61, s60, 31
	s_lshl_b64 s[60:61], s[60:61], 1
	s_add_u32 s60, s64, s60
	s_addc_u32 s61, s65, s61
	s_ashr_i32 s6, s31, 2
	s_andn2_b32 s6, s6, 63
	v_and_or_b32 v158, v132, 15, s6
	s_lshl_b32 s6, s36, 5
	v_lshlrev_b32_e32 v96, 4, v132
	s_and_b32 s6, s6, 0x60
	v_lshrrev_b32_e32 v132, 1, v132
	v_and_b32_e32 v96, 0x3f0, v96
	v_and_b32_e32 v171, 15, v212
	v_lshlrev_b32_e32 v171, 9, v171
	v_and_b32_e32 v172, 0xf0, v212
	v_or_b32_e32 v171, v171, v172
	v_and_b32_e32 v172, 0x100, v212
	v_lshlrev_b32_e32 v172, 7, v172
	v_or_b32_e32 v170, v171, v172
	v_and_or_b32 v159, v132, 24, s6
	v_mov_b32_e32 v171, v170
	global_load_dwordx4 v[160:163], v171, s[62:63]
	v_add_u32_e32 v171, 0x100, v170
	global_load_dwordx4 v[164:167], v171, s[62:63]
	v_add_u32_e32 v171, 0x2000, v170
	global_load_dwordx4 v[152:155], v171, s[62:63]
	v_add_u32_e32 v171, 0x2100, v170
	global_load_dwordx4 v[148:151], v171, s[62:63]
	v_lshl_add_u64 v[98:99], s[62:63], 0, v[96:97]
	s_movk_i32 s6, 0x1000
	v_add_co_u32_e32 v132, vcc, s6, v98
	s_movk_i32 s6, 0x2000
	s_nop 0
	v_addc_co_u32_e32 v133, vcc, 0, v99, vcc
	v_add_co_u32_e32 v156, vcc, s6, v98
	v_lshlrev_b32_e32 v96, 1, v159
	s_nop 0
	v_addc_co_u32_e32 v157, vcc, 0, v99, vcc
	v_add_u32_e32 v171, 0x4000, v170
	global_load_dwordx4 v[144:147], v171, s[62:63]
	v_add_u32_e32 v171, 0x4100, v170
	global_load_dwordx4 v[140:143], v171, s[62:63]
	v_add_u32_e32 v171, 0x6000, v170
	global_load_dwordx4 v[136:139], v171, s[62:63]
	s_nop 0
	v_add_u32_e32 v171, 0x6100, v170
	global_load_dwordx4 v[132:135], v171, s[62:63]
	v_lshl_add_u32 v96, v158, 11, v96
	s_movk_i32 s6, 0x3000
	s_waitcnt vmcnt(0)
	v_lshlrev_b32_e32 v168, 16, v160
	v_and_b32_e32 v160, 0xffff0000, v160
	v_rcp_f32_e32 v168, v168
	v_rcp_f32_e32 v169, v160
	s_nop 0
	v_pk_mul_f32 v[128:129], v[128:129], v[168:169]
	s_nop 0
	v_cvt_pk_bf16_f32 v128, v128, v129
	v_lshlrev_b32_e32 v129, 16, v161
	v_rcp_f32_e32 v160, v129
	v_and_b32_e32 v129, 0xffff0000, v161
	v_rcp_f32_e32 v161, v129
	s_nop 0
	v_pk_mul_f32 v[130:131], v[130:131], v[160:161]
	s_nop 0
	v_cvt_pk_bf16_f32 v129, v130, v131
	v_lshlrev_b32_e32 v130, 16, v162
	v_and_b32_e32 v131, 0xffff0000, v162
	v_rcp_f32_e32 v130, v130
	v_rcp_f32_e32 v131, v131
	s_nop 0
	v_pk_mul_f32 v[120:121], v[120:121], v[130:131]
	s_nop 0
	v_cvt_pk_bf16_f32 v130, v120, v121
	v_lshlrev_b32_e32 v120, 16, v163
	v_and_b32_e32 v121, 0xffff0000, v163
	v_rcp_f32_e32 v120, v120
	v_rcp_f32_e32 v121, v121
	s_nop 0
	v_pk_mul_f32 v[120:121], v[122:123], v[120:121]
	s_nop 0
	v_cvt_pk_bf16_f32 v131, v120, v121
	v_lshlrev_b32_e32 v120, 16, v164
	v_and_b32_e32 v121, 0xffff0000, v164
	v_rcp_f32_e32 v120, v120
	v_rcp_f32_e32 v121, v121
	global_store_dwordx4 v96, v[128:131], s[60:61]
	v_pk_mul_f32 v[120:121], v[124:125], v[120:121]
	s_nop 0
	v_cvt_pk_bf16_f32 v120, v120, v121
	v_lshlrev_b32_e32 v121, 16, v165
	v_rcp_f32_e32 v122, v121
	v_and_b32_e32 v121, 0xffff0000, v165
	v_rcp_f32_e32 v123, v121
	s_nop 0
	v_pk_mul_f32 v[122:123], v[126:127], v[122:123]
	s_nop 0
	v_cvt_pk_bf16_f32 v121, v122, v123
	v_lshlrev_b32_e32 v122, 16, v166
	v_and_b32_e32 v123, 0xffff0000, v166
	v_rcp_f32_e32 v122, v122
	v_rcp_f32_e32 v123, v123
	s_nop 0
	v_pk_mul_f32 v[116:117], v[116:117], v[122:123]
	s_nop 0
	v_cvt_pk_bf16_f32 v122, v116, v117
	v_lshlrev_b32_e32 v116, 16, v167
	v_and_b32_e32 v117, 0xffff0000, v167
	v_rcp_f32_e32 v116, v116
	v_rcp_f32_e32 v117, v117
	s_nop 0
	v_pk_mul_f32 v[116:117], v[118:119], v[116:117]
	s_nop 0
	v_cvt_pk_bf16_f32 v123, v116, v117
	v_add_u32_e32 v116, 0x100, v96
	global_store_dwordx4 v116, v[120:123], s[60:61]
	v_lshlrev_b32_e32 v116, 16, v152
	v_and_b32_e32 v117, 0xffff0000, v152
	v_rcp_f32_e32 v116, v116
	v_rcp_f32_e32 v117, v117
	v_add_u32_e32 v118, 0x8000, v96
	v_pk_mul_f32 v[112:113], v[112:113], v[116:117]
	s_nop 0
	v_cvt_pk_bf16_f32 v112, v112, v113
	v_lshlrev_b32_e32 v113, 16, v153
	v_rcp_f32_e32 v116, v113
	v_and_b32_e32 v113, 0xffff0000, v153
	v_rcp_f32_e32 v117, v113
	s_nop 0
	v_pk_mul_f32 v[114:115], v[114:115], v[116:117]
	s_nop 0
	v_cvt_pk_bf16_f32 v113, v114, v115
	v_lshlrev_b32_e32 v114, 16, v154
	v_and_b32_e32 v115, 0xffff0000, v154
	v_rcp_f32_e32 v114, v114
	v_rcp_f32_e32 v115, v115
	s_nop 0
	v_pk_mul_f32 v[108:109], v[108:109], v[114:115]
	s_nop 0
	v_cvt_pk_bf16_f32 v114, v108, v109
	v_lshlrev_b32_e32 v108, 16, v155
	v_and_b32_e32 v109, 0xffff0000, v155
	v_rcp_f32_e32 v108, v108
	v_rcp_f32_e32 v109, v109
	s_nop 0
	v_pk_mul_f32 v[108:109], v[110:111], v[108:109]
	s_nop 0
	v_cvt_pk_bf16_f32 v115, v108, v109
	v_lshlrev_b32_e32 v108, 16, v148
	v_and_b32_e32 v109, 0xffff0000, v148
	v_rcp_f32_e32 v108, v108
	v_rcp_f32_e32 v109, v109
	global_store_dwordx4 v118, v[112:115], s[60:61]
	v_pk_mul_f32 v[104:105], v[104:105], v[108:109]
	s_nop 0
	v_cvt_pk_bf16_f32 v104, v104, v105
	v_lshlrev_b32_e32 v105, 16, v149
	v_rcp_f32_e32 v108, v105
	v_and_b32_e32 v105, 0xffff0000, v149
	v_rcp_f32_e32 v109, v105
	s_nop 0
	v_pk_mul_f32 v[106:107], v[106:107], v[108:109]
	s_nop 0
	v_cvt_pk_bf16_f32 v105, v106, v107
	v_lshlrev_b32_e32 v106, 16, v150
	v_and_b32_e32 v107, 0xffff0000, v150
	v_rcp_f32_e32 v106, v106
	v_rcp_f32_e32 v107, v107
	s_nop 0
	v_pk_mul_f32 v[100:101], v[100:101], v[106:107]
	s_nop 0
; __device__ __forceinline__ float bf_lo(unsigned w) { return __uint_as_float(w << 16); }
; __device__ __forceinline__ float bf_hi(unsigned w) { return __uint_as_float(w & 0xffff0000u); }
; __device__ __forceinline__ unsigned cvt_pk_bf16(float lo, float hi) { f32x2_t v = {lo, hi}; bf16x2_t b = __builtin_convertvector(v, bf16x2_t); return __builtin_bit_cast(unsigned, b); }
;     __device__ __forceinline__ void operator()(const f32x4 (&acc)[2][2][4][2], const Unit& u, int wr, int wc, int fr, int fq) const {
;     ...
;         for (int ai = 0; ai < 2; ++ai) {
;             u32x4 gv[4][2];
; #pragma unroll
;             for (int m = 0; m < 4; ++m)
; #pragma unroll
;                 for (int bj = 0; bj < 2; ++bj) gv[m][bj] = *(const u32x4*)(g_b + ((ai * 4 + m) * 2 + bj) * 1024);
; #pragma unroll
;             for (int m = 0; m < 4; ++m) { const unsigned rl = rl0 + (unsigned)(ai * HALF + m * 16);
; #pragma unroll
;                 for (int bj = 0; bj < 2; ++bj) { const unsigned cl = cl0 + (unsigned)(bj * HALF);
;                     const u32x4 g = gv[m][bj];
;                     const f32x4 v0 = acc[ai][bj][m][0], v1 = acc[ai][bj][m][1];
;                     u32x4 w;
;                     w.x = cvt_pk_bf16(v0[0] * __builtin_amdgcn_rcpf(bf_lo(g.x)), v0[1] * __builtin_amdgcn_rcpf(bf_hi(g.x)));
;                     w.y = cvt_pk_bf16(v0[2] * __builtin_amdgcn_rcpf(bf_lo(g.y)), v0[3] * __builtin_amdgcn_rcpf(bf_hi(g.y)));
;                     w.z = cvt_pk_bf16(v1[0] * __builtin_amdgcn_rcpf(bf_lo(g.z)), v1[1] * __builtin_amdgcn_rcpf(bf_hi(g.z)));
;                     w.w = cvt_pk_bf16(v1[2] * __builtin_amdgcn_rcpf(bf_lo(g.w)), v1[3] * __builtin_amdgcn_rcpf(bf_hi(g.w)));
;                     *(u32x4*)(mb + (rl * 1024u + cl) * 2u) = w; } }
;             asm volatile("" : "+v"(rl0), "+v"(cl0) :: "memory"); }
	v_cvt_pk_bf16_f32 v106, v100, v101
	v_lshlrev_b32_e32 v100, 16, v151
	v_and_b32_e32 v101, 0xffff0000, v151
	v_rcp_f32_e32 v100, v100
	v_rcp_f32_e32 v101, v101
	s_nop 0
	v_pk_mul_f32 v[100:101], v[102:103], v[100:101]
	s_nop 0
	v_cvt_pk_bf16_f32 v107, v100, v101
	v_add_u32_e32 v100, 0x8100, v96
	global_store_dwordx4 v100, v[104:107], s[60:61]
	v_lshlrev_b32_e32 v100, 16, v144
	v_and_b32_e32 v101, 0xffff0000, v144
	v_rcp_f32_e32 v100, v100
	v_rcp_f32_e32 v101, v101
	v_add_u32_e32 v102, 0x10000, v96
	v_pk_mul_f32 v[92:93], v[92:93], v[100:101]
	s_nop 0
	v_cvt_pk_bf16_f32 v92, v92, v93
	v_lshlrev_b32_e32 v93, 16, v145
	v_rcp_f32_e32 v100, v93
	v_and_b32_e32 v93, 0xffff0000, v145
	v_rcp_f32_e32 v101, v93
	s_nop 0
	v_pk_mul_f32 v[94:95], v[94:95], v[100:101]
	s_nop 0
	v_cvt_pk_bf16_f32 v93, v94, v95
	v_lshlrev_b32_e32 v94, 16, v146
	v_and_b32_e32 v95, 0xffff0000, v146
	v_rcp_f32_e32 v94, v94
	v_rcp_f32_e32 v95, v95
	s_nop 0
	v_pk_mul_f32 v[88:89], v[88:89], v[94:95]
	s_nop 0
	v_cvt_pk_bf16_f32 v94, v88, v89
	v_lshlrev_b32_e32 v88, 16, v147
	v_and_b32_e32 v89, 0xffff0000, v147
	v_rcp_f32_e32 v88, v88
	v_rcp_f32_e32 v89, v89
	s_nop 0
	v_pk_mul_f32 v[88:89], v[90:91], v[88:89]
	s_nop 0
	v_cvt_pk_bf16_f32 v95, v88, v89
	v_lshlrev_b32_e32 v88, 16, v140
	v_and_b32_e32 v89, 0xffff0000, v140
	v_rcp_f32_e32 v88, v88
	v_rcp_f32_e32 v89, v89
	global_store_dwordx4 v102, v[92:95], s[60:61]
	v_pk_mul_f32 v[84:85], v[84:85], v[88:89]
	s_nop 0
	v_cvt_pk_bf16_f32 v84, v84, v85
	v_lshlrev_b32_e32 v85, 16, v141
	v_rcp_f32_e32 v88, v85
	v_and_b32_e32 v85, 0xffff0000, v141
	v_rcp_f32_e32 v89, v85
	s_nop 0
	v_pk_mul_f32 v[86:87], v[86:87], v[88:89]
	s_nop 0
	v_cvt_pk_bf16_f32 v85, v86, v87
	v_lshlrev_b32_e32 v86, 16, v142
	v_and_b32_e32 v87, 0xffff0000, v142
	v_rcp_f32_e32 v86, v86
	v_rcp_f32_e32 v87, v87
	s_nop 0
	v_pk_mul_f32 v[80:81], v[80:81], v[86:87]
	s_nop 0
	v_cvt_pk_bf16_f32 v86, v80, v81
	v_lshlrev_b32_e32 v80, 16, v143
	v_and_b32_e32 v81, 0xffff0000, v143
	v_rcp_f32_e32 v80, v80
	v_rcp_f32_e32 v81, v81
	s_nop 0
	v_pk_mul_f32 v[80:81], v[82:83], v[80:81]
	s_nop 0
	v_cvt_pk_bf16_f32 v87, v80, v81
	v_add_u32_e32 v80, 0x10100, v96
	global_store_dwordx4 v80, v[84:87], s[60:61]
	v_lshlrev_b32_e32 v80, 16, v136
	v_and_b32_e32 v81, 0xffff0000, v136
	v_rcp_f32_e32 v80, v80
	v_rcp_f32_e32 v81, v81
	v_add_u32_e32 v82, 0x18000, v96
	v_pk_mul_f32 v[76:77], v[76:77], v[80:81]
	s_nop 0
	v_cvt_pk_bf16_f32 v76, v76, v77
	v_lshlrev_b32_e32 v77, 16, v137
	v_rcp_f32_e32 v80, v77
	v_and_b32_e32 v77, 0xffff0000, v137
	v_rcp_f32_e32 v81, v77
	s_nop 0
	v_pk_mul_f32 v[78:79], v[78:79], v[80:81]
	s_nop 0
	v_cvt_pk_bf16_f32 v77, v78, v79
	v_lshlrev_b32_e32 v78, 16, v138
	v_and_b32_e32 v79, 0xffff0000, v138
	v_rcp_f32_e32 v78, v78
	v_rcp_f32_e32 v79, v79
	s_nop 0
	v_pk_mul_f32 v[72:73], v[72:73], v[78:79]
	s_nop 0
	v_cvt_pk_bf16_f32 v78, v72, v73
	v_lshlrev_b32_e32 v72, 16, v139
	v_and_b32_e32 v73, 0xffff0000, v139
	v_rcp_f32_e32 v72, v72
	v_rcp_f32_e32 v73, v73
	s_nop 0
	v_pk_mul_f32 v[72:73], v[74:75], v[72:73]
	s_nop 0
	v_cvt_pk_bf16_f32 v79, v72, v73
	v_lshlrev_b32_e32 v72, 16, v132
	v_and_b32_e32 v73, 0xffff0000, v132
	v_rcp_f32_e32 v72, v72
	v_rcp_f32_e32 v73, v73
	global_store_dwordx4 v82, v[76:79], s[60:61]
	v_pk_mul_f32 v[68:69], v[68:69], v[72:73]
	s_nop 0
	v_cvt_pk_bf16_f32 v68, v68, v69
	v_lshlrev_b32_e32 v69, 16, v133
	v_rcp_f32_e32 v72, v69
	v_and_b32_e32 v69, 0xffff0000, v133
	v_rcp_f32_e32 v73, v69
	s_nop 0
	v_pk_mul_f32 v[70:71], v[70:71], v[72:73]
	s_nop 0
	v_cvt_pk_bf16_f32 v69, v70, v71
	v_lshlrev_b32_e32 v70, 16, v134
	v_and_b32_e32 v71, 0xffff0000, v134
	v_rcp_f32_e32 v70, v70
	v_rcp_f32_e32 v71, v71
	s_nop 0
	v_pk_mul_f32 v[64:65], v[64:65], v[70:71]
	s_nop 0
	v_cvt_pk_bf16_f32 v70, v64, v65
	v_lshlrev_b32_e32 v64, 16, v135
	v_and_b32_e32 v65, 0xffff0000, v135
	v_rcp_f32_e32 v64, v64
	v_rcp_f32_e32 v65, v65
	s_nop 0
	v_pk_mul_f32 v[64:65], v[66:67], v[64:65]
	s_nop 0
	v_cvt_pk_bf16_f32 v71, v64, v65
	v_add_u32_e32 v64, 0x18100, v96
	global_store_dwordx4 v64, v[68:71], s[60:61]
	v_add_u32_e32 v171, 0x10000, v170
	global_load_dwordx4 v[90:93], v171, s[62:63]
	v_add_u32_e32 v171, 0x10100, v170
	global_load_dwordx4 v[100:103], v171, s[62:63]
	v_add_u32_e32 v171, 0x12000, v170
	global_load_dwordx4 v[84:87], v171, s[62:63]
	v_add_u32_e32 v171, 0x12100, v170
	global_load_dwordx4 v[80:83], v171, s[62:63]
	v_add_co_u32_e32 v64, vcc, s6, v98
	v_lshlrev_b32_e32 v88, 11, v158
	s_nop 0
	v_addc_co_u32_e32 v65, vcc, 0, v99, vcc
	v_add_u32_e32 v171, 0x14000, v170
	global_load_dwordx4 v[76:79], v171, s[62:63]
	v_add_u32_e32 v171, 0x14100, v170
	global_load_dwordx4 v[72:75], v171, s[62:63]
	v_add_u32_e32 v171, 0x16000, v170
	global_load_dwordx4 v[68:71], v171, s[62:63]
	s_nop 0
	v_add_u32_e32 v171, 0x16100, v170
	global_load_dwordx4 v[64:67], v171, s[62:63]
	v_lshl_add_u32 v88, v159, 1, v88
	v_add_u32_e32 v89, 0x40000, v88
	s_and_b64 vcc, exec, s[38:39]
	s_waitcnt vmcnt(0)
; __device__ __forceinline__ float bf_lo(unsigned w) { return __uint_as_float(w << 16); }
; __device__ __forceinline__ float bf_hi(unsigned w) { return __uint_as_float(w & 0xffff0000u); }
; __device__ __forceinline__ unsigned cvt_pk_bf16(float lo, float hi) { f32x2_t v = {lo, hi}; bf16x2_t b = __builtin_convertvector(v, bf16x2_t); return __builtin_bit_cast(unsigned, b); }
;     __device__ __forceinline__ void operator()(const f32x4 (&acc)[2][2][4][2], const Unit& u, int wr, int wc, int fr, int fq) const {
;     ...
;             for (int m = 0; m < 4; ++m) { const unsigned rl = rl0 + (unsigned)(ai * HALF + m * 16);
; #pragma unroll
;                 for (int bj = 0; bj < 2; ++bj) { const unsigned cl = cl0 + (unsigned)(bj * HALF);
;                     const u32x4 g = gv[m][bj];
;                     const f32x4 v0 = acc[ai][bj][m][0], v1 = acc[ai][bj][m][1];
;                     u32x4 w;
;                     w.x = cvt_pk_bf16(v0[0] * __builtin_amdgcn_rcpf(bf_lo(g.x)), v0[1] * __builtin_amdgcn_rcpf(bf_hi(g.x)));
;                     w.y = cvt_pk_bf16(v0[2] * __builtin_amdgcn_rcpf(bf_lo(g.y)), v0[3] * __builtin_amdgcn_rcpf(bf_hi(g.y)));
;                     w.z = cvt_pk_bf16(v1[0] * __builtin_amdgcn_rcpf(bf_lo(g.z)), v1[1] * __builtin_amdgcn_rcpf(bf_hi(g.z)));
;                     w.w = cvt_pk_bf16(v1[2] * __builtin_amdgcn_rcpf(bf_lo(g.w)), v1[3] * __builtin_amdgcn_rcpf(bf_hi(g.w)));
;                     *(u32x4*)(mb + (rl * 1024u + cl) * 2u) = w; } }
	v_lshlrev_b32_e32 v94, 16, v90
	v_and_b32_e32 v90, 0xffff0000, v90
	v_rcp_f32_e32 v94, v94
	v_rcp_f32_e32 v95, v90
	s_nop 0
	v_pk_mul_f32 v[60:61], v[60:61], v[94:95]
	s_nop 0
	v_cvt_pk_bf16_f32 v60, v60, v61
	v_lshlrev_b32_e32 v61, 16, v91
	v_rcp_f32_e32 v90, v61
	v_and_b32_e32 v61, 0xffff0000, v91
	v_rcp_f32_e32 v91, v61
	s_nop 0
	v_pk_mul_f32 v[62:63], v[62:63], v[90:91]
	s_nop 0
	v_cvt_pk_bf16_f32 v61, v62, v63
	v_lshlrev_b32_e32 v62, 16, v92
	v_and_b32_e32 v63, 0xffff0000, v92
	v_rcp_f32_e32 v62, v62
	v_rcp_f32_e32 v63, v63
	s_nop 0
	v_pk_mul_f32 v[56:57], v[56:57], v[62:63]
	s_nop 0
	v_cvt_pk_bf16_f32 v62, v56, v57
	v_lshlrev_b32_e32 v56, 16, v93
	v_and_b32_e32 v57, 0xffff0000, v93
	v_rcp_f32_e32 v56, v56
	v_rcp_f32_e32 v57, v57
	s_nop 0
	v_pk_mul_f32 v[56:57], v[58:59], v[56:57]
	s_nop 0
	v_cvt_pk_bf16_f32 v63, v56, v57
	v_lshlrev_b32_e32 v56, 16, v100
	v_and_b32_e32 v57, 0xffff0000, v100
	v_rcp_f32_e32 v56, v56
	v_rcp_f32_e32 v57, v57
	global_store_dwordx4 v89, v[60:63], s[60:61]
	v_pk_mul_f32 v[52:53], v[52:53], v[56:57]
	s_nop 0
	v_cvt_pk_bf16_f32 v52, v52, v53
	v_lshlrev_b32_e32 v53, 16, v101
	v_rcp_f32_e32 v56, v53
	v_and_b32_e32 v53, 0xffff0000, v101
	v_rcp_f32_e32 v57, v53
	s_nop 0
	v_pk_mul_f32 v[54:55], v[54:55], v[56:57]
	s_nop 0
	v_cvt_pk_bf16_f32 v53, v54, v55
	v_lshlrev_b32_e32 v54, 16, v102
	v_and_b32_e32 v55, 0xffff0000, v102
	v_rcp_f32_e32 v54, v54
	v_rcp_f32_e32 v55, v55
	s_nop 0
	v_pk_mul_f32 v[48:49], v[48:49], v[54:55]
	s_nop 0
	v_cvt_pk_bf16_f32 v54, v48, v49
	v_lshlrev_b32_e32 v48, 16, v103
	v_and_b32_e32 v49, 0xffff0000, v103
	v_rcp_f32_e32 v48, v48
	v_rcp_f32_e32 v49, v49
	s_nop 0
	v_pk_mul_f32 v[48:49], v[50:51], v[48:49]
	s_nop 0
	v_cvt_pk_bf16_f32 v55, v48, v49
	v_add_u32_e32 v48, 0x40100, v88
	global_store_dwordx4 v48, v[52:55], s[60:61]
	v_lshlrev_b32_e32 v48, 16, v84
	v_and_b32_e32 v49, 0xffff0000, v84
	v_rcp_f32_e32 v48, v48
	v_rcp_f32_e32 v49, v49
	v_add_u32_e32 v50, 0x48000, v88
	v_pk_mul_f32 v[44:45], v[44:45], v[48:49]
	s_nop 0
	v_cvt_pk_bf16_f32 v44, v44, v45
	v_lshlrev_b32_e32 v45, 16, v85
	v_rcp_f32_e32 v48, v45
	v_and_b32_e32 v45, 0xffff0000, v85
	v_rcp_f32_e32 v49, v45
	s_nop 0
	v_pk_mul_f32 v[46:47], v[46:47], v[48:49]
	s_nop 0
	v_cvt_pk_bf16_f32 v45, v46, v47
	v_lshlrev_b32_e32 v46, 16, v86
	v_and_b32_e32 v47, 0xffff0000, v86
	v_rcp_f32_e32 v46, v46
	v_rcp_f32_e32 v47, v47
	s_nop 0
	v_pk_mul_f32 v[40:41], v[40:41], v[46:47]
	s_nop 0
	v_cvt_pk_bf16_f32 v46, v40, v41
	v_lshlrev_b32_e32 v40, 16, v87
	v_and_b32_e32 v41, 0xffff0000, v87
	v_rcp_f32_e32 v40, v40
	v_rcp_f32_e32 v41, v41
	s_nop 0
	v_pk_mul_f32 v[40:41], v[42:43], v[40:41]
	s_nop 0
	v_cvt_pk_bf16_f32 v47, v40, v41
	v_lshlrev_b32_e32 v40, 16, v80
	v_and_b32_e32 v41, 0xffff0000, v80
	v_rcp_f32_e32 v40, v40
	v_rcp_f32_e32 v41, v41
	global_store_dwordx4 v50, v[44:47], s[60:61]
	v_pk_mul_f32 v[36:37], v[36:37], v[40:41]
	s_nop 0
	v_cvt_pk_bf16_f32 v36, v36, v37
	v_lshlrev_b32_e32 v37, 16, v81
	v_rcp_f32_e32 v40, v37
	v_and_b32_e32 v37, 0xffff0000, v81
	v_rcp_f32_e32 v41, v37
	s_nop 0
	v_pk_mul_f32 v[38:39], v[38:39], v[40:41]
	s_nop 0
	v_cvt_pk_bf16_f32 v37, v38, v39
	v_lshlrev_b32_e32 v38, 16, v82
	v_and_b32_e32 v39, 0xffff0000, v82
	v_rcp_f32_e32 v38, v38
	v_rcp_f32_e32 v39, v39
	s_nop 0
	v_pk_mul_f32 v[32:33], v[32:33], v[38:39]
	s_nop 0
	v_cvt_pk_bf16_f32 v38, v32, v33
	v_lshlrev_b32_e32 v32, 16, v83
	v_and_b32_e32 v33, 0xffff0000, v83
	v_rcp_f32_e32 v32, v32
	v_rcp_f32_e32 v33, v33
	s_nop 0
	v_pk_mul_f32 v[32:33], v[34:35], v[32:33]
	s_nop 0
	v_cvt_pk_bf16_f32 v39, v32, v33
	v_add_u32_e32 v32, 0x48100, v88
	global_store_dwordx4 v32, v[36:39], s[60:61]
	v_lshlrev_b32_e32 v32, 16, v76
; __device__ __forceinline__ float bf_lo(unsigned w) { return __uint_as_float(w << 16); }
; __device__ __forceinline__ float bf_hi(unsigned w) { return __uint_as_float(w & 0xffff0000u); }
; __device__ __forceinline__ unsigned cvt_pk_bf16(float lo, float hi) { f32x2_t v = {lo, hi}; bf16x2_t b = __builtin_convertvector(v, bf16x2_t); return __builtin_bit_cast(unsigned, b); }
; #define PG8_BAR __builtin_amdgcn_s_barrier()
;     __device__ __forceinline__ void operator()(const f32x4 (&acc)[2][2][4][2], const Unit& u, int wr, int wc, int fr, int fq) const {
;     ...
;             for (int m = 0; m < 4; ++m) { const unsigned rl = rl0 + (unsigned)(ai * HALF + m * 16);
; #pragma unroll
;                 for (int bj = 0; bj < 2; ++bj) { const unsigned cl = cl0 + (unsigned)(bj * HALF);
;                     const u32x4 g = gv[m][bj];
;                     const f32x4 v0 = acc[ai][bj][m][0], v1 = acc[ai][bj][m][1];
;                     u32x4 w;
;                     w.x = cvt_pk_bf16(v0[0] * __builtin_amdgcn_rcpf(bf_lo(g.x)), v0[1] * __builtin_amdgcn_rcpf(bf_hi(g.x)));
;                     w.y = cvt_pk_bf16(v0[2] * __builtin_amdgcn_rcpf(bf_lo(g.y)), v0[3] * __builtin_amdgcn_rcpf(bf_hi(g.y)));
;                     w.z = cvt_pk_bf16(v1[0] * __builtin_amdgcn_rcpf(bf_lo(g.z)), v1[1] * __builtin_amdgcn_rcpf(bf_hi(g.z)));
;                     w.w = cvt_pk_bf16(v1[2] * __builtin_amdgcn_rcpf(bf_lo(g.w)), v1[3] * __builtin_amdgcn_rcpf(bf_hi(g.w)));
;                     *(u32x4*)(mb + (rl * 1024u + cl) * 2u) = w; } }
;             asm volatile("" : "+v"(rl0), "+v"(cl0) :: "memory"); }
; template <class Epi, class Sched, bool ALIGN_EPI = false, bool SP2 = false>
; __device__ __forceinline__ void gemm_phase(PG8_LAS unsigned char* lds, const Gemm g, const Sched& S, const Epi& E) {
;     ...
;         if (!has_next) break;
;         if constexpr (Epi::ACC_INIT) E.acc_init(ini, nxt);
; #pragma unroll
;         for (int a = 0; a < 2; ++a)
; #pragma unroll
;             for (int b = 0; b < 2; ++b)
; #pragma unroll
;                 for (int m = 0; m < 4; ++m)
; #pragma unroll
;                     for (int n = 0; n < 2; ++n) acc[a][b][m][n] = ini[b][n];
;         cur = nxt; cA = nA; cB = nB; ++ui;
;         if constexpr (ALIGN_EPI) { if (wr == 1) PG8_BAR; }
	v_and_b32_e32 v33, 0xffff0000, v76
	v_rcp_f32_e32 v32, v32
	v_rcp_f32_e32 v33, v33
	v_add_u32_e32 v34, 0x50000, v88
	v_pk_mul_f32 v[28:29], v[28:29], v[32:33]
	s_nop 0
	v_cvt_pk_bf16_f32 v28, v28, v29
	v_lshlrev_b32_e32 v29, 16, v77
	v_rcp_f32_e32 v32, v29
	v_and_b32_e32 v29, 0xffff0000, v77
	v_rcp_f32_e32 v33, v29
	s_nop 0
	v_pk_mul_f32 v[30:31], v[30:31], v[32:33]
	s_nop 0
	v_cvt_pk_bf16_f32 v29, v30, v31
	v_lshlrev_b32_e32 v30, 16, v78
	v_and_b32_e32 v31, 0xffff0000, v78
	v_rcp_f32_e32 v30, v30
	v_rcp_f32_e32 v31, v31
	s_nop 0
	v_pk_mul_f32 v[24:25], v[24:25], v[30:31]
	s_nop 0
	v_cvt_pk_bf16_f32 v30, v24, v25
	v_lshlrev_b32_e32 v24, 16, v79
	v_and_b32_e32 v25, 0xffff0000, v79
	v_rcp_f32_e32 v24, v24
	v_rcp_f32_e32 v25, v25
	s_nop 0
	v_pk_mul_f32 v[24:25], v[26:27], v[24:25]
	s_nop 0
	v_cvt_pk_bf16_f32 v31, v24, v25
	v_lshlrev_b32_e32 v24, 16, v72
	v_and_b32_e32 v25, 0xffff0000, v72
	v_rcp_f32_e32 v24, v24
	v_rcp_f32_e32 v25, v25
	global_store_dwordx4 v34, v[28:31], s[60:61]
	v_pk_mul_f32 v[20:21], v[20:21], v[24:25]
	s_nop 0
	v_cvt_pk_bf16_f32 v20, v20, v21
	v_lshlrev_b32_e32 v21, 16, v73
	v_rcp_f32_e32 v24, v21
	v_and_b32_e32 v21, 0xffff0000, v73
	v_rcp_f32_e32 v25, v21
	s_nop 0
	v_pk_mul_f32 v[22:23], v[22:23], v[24:25]
	s_nop 0
	v_cvt_pk_bf16_f32 v21, v22, v23
	v_lshlrev_b32_e32 v22, 16, v74
	v_and_b32_e32 v23, 0xffff0000, v74
	v_rcp_f32_e32 v22, v22
	v_rcp_f32_e32 v23, v23
	s_nop 0
	v_pk_mul_f32 v[12:13], v[12:13], v[22:23]
	s_nop 0
	v_cvt_pk_bf16_f32 v22, v12, v13
	v_lshlrev_b32_e32 v12, 16, v75
	v_and_b32_e32 v13, 0xffff0000, v75
	v_rcp_f32_e32 v12, v12
	v_rcp_f32_e32 v13, v13
	s_nop 0
	v_pk_mul_f32 v[12:13], v[14:15], v[12:13]
	s_nop 0
	v_cvt_pk_bf16_f32 v23, v12, v13
	v_add_u32_e32 v12, 0x50100, v88
	global_store_dwordx4 v12, v[20:23], s[60:61]
	v_lshlrev_b32_e32 v12, 16, v68
	v_and_b32_e32 v13, 0xffff0000, v68
	v_rcp_f32_e32 v12, v12
	v_rcp_f32_e32 v13, v13
	v_add_u32_e32 v20, 0x58000, v88
	v_pk_mul_f32 v[12:13], v[16:17], v[12:13]
	s_nop 0
	v_cvt_pk_bf16_f32 v12, v12, v13
	v_lshlrev_b32_e32 v13, 16, v69
	v_rcp_f32_e32 v14, v13
	v_and_b32_e32 v13, 0xffff0000, v69
	v_rcp_f32_e32 v15, v13
	s_nop 0
	v_pk_mul_f32 v[14:15], v[18:19], v[14:15]
	s_nop 0
	v_cvt_pk_bf16_f32 v13, v14, v15
	v_lshlrev_b32_e32 v14, 16, v70
	v_and_b32_e32 v15, 0xffff0000, v70
	v_rcp_f32_e32 v14, v14
	v_rcp_f32_e32 v15, v15
	s_nop 0
	v_pk_mul_f32 v[8:9], v[8:9], v[14:15]
	s_nop 0
	v_cvt_pk_bf16_f32 v14, v8, v9
	v_lshlrev_b32_e32 v8, 16, v71
	v_and_b32_e32 v9, 0xffff0000, v71
	v_rcp_f32_e32 v8, v8
	v_rcp_f32_e32 v9, v9
	s_nop 0
	v_pk_mul_f32 v[8:9], v[10:11], v[8:9]
	s_nop 0
	v_cvt_pk_bf16_f32 v15, v8, v9
	v_lshlrev_b32_e32 v8, 16, v64
	v_and_b32_e32 v9, 0xffff0000, v64
	v_rcp_f32_e32 v8, v8
	v_rcp_f32_e32 v9, v9
	global_store_dwordx4 v20, v[12:15], s[60:61]
	v_pk_mul_f32 v[4:5], v[4:5], v[8:9]
	s_nop 0
	v_cvt_pk_bf16_f32 v4, v4, v5
	v_lshlrev_b32_e32 v5, 16, v65
	v_rcp_f32_e32 v8, v5
	v_and_b32_e32 v5, 0xffff0000, v65
	v_rcp_f32_e32 v9, v5
	s_nop 0
	v_pk_mul_f32 v[6:7], v[6:7], v[8:9]
	s_nop 0
	v_cvt_pk_bf16_f32 v5, v6, v7
	v_lshlrev_b32_e32 v6, 16, v66
	v_and_b32_e32 v7, 0xffff0000, v66
	v_rcp_f32_e32 v6, v6
	v_rcp_f32_e32 v7, v7
	s_nop 0
	v_pk_mul_f32 v[0:1], v[0:1], v[6:7]
	s_nop 0
	v_cvt_pk_bf16_f32 v6, v0, v1
	v_lshlrev_b32_e32 v0, 16, v67
	v_and_b32_e32 v1, 0xffff0000, v67
	v_rcp_f32_e32 v0, v0
	v_rcp_f32_e32 v1, v1
	s_nop 0
	v_pk_mul_f32 v[0:1], v[2:3], v[0:1]
	s_nop 0
	v_cvt_pk_bf16_f32 v7, v0, v1
	v_add_u32_e32 v0, 0x58100, v88
	global_store_dwordx4 v0, v[4:7], s[60:61]
	s_mov_b64 s[60:61], -1
	s_cbranch_vccnz .LBB0_35
	s_andn2_b64 vcc, exec, s[46:47]
	s_cbranch_vccnz .LBB0_34
	s_barrier
	s_branch .LBB0_34

; __device__ __forceinline__ unsigned cvt_pk_bf16(float lo, float hi) { f32x2_t v = {lo, hi}; bf16x2_t b = __builtin_convertvector(v, bf16x2_t); return __builtin_bit_cast(unsigned, b); }
; template <int MODE> __device__ __forceinline__ float actf(float v) {
;     ...
;     if (MODE == 2) return fminf(1.0f + __builtin_amdgcn_exp2f(-LOG2E * v), 1e30f);
;     template <int MODE> __device__ __forceinline__ void run(const f32x4 (&acc)[2][2][4][2], const Unit& u, int wr, int wc, int fr, int fq) const {
;     ...
;         char* base = (MODE == 2) ? (char*)(O + (size_t)6 * ((size_t)MTOK * 512)) + ((size_t)(((pn - 12) * 128 + u.pm) * 8 + wid__)) * 16384
;                                  : (char*)(O + (size_t)t * ((size_t)MTOK * 512) + (size_t)u.pm * BM * 512 + (colt & 511));
;         unsigned off0 = (MODE == 2) ? (unsigned)((t__ & 63) * 16) : (unsigned)((wr * 64 + fr) * 512 + wc * 32 + 8 * fq) * 2u; asm volatile("" : "+v"(off0));
; #pragma unroll
;         for (int bj = 0; bj < 2; ++bj) {
; #pragma unroll
;             for (int ai = 0; ai < 2; ++ai)
; #pragma unroll
;                 for (int m = 0; m < 4; ++m) { const unsigned off = off0 + ((MODE == 2) ? (unsigned)(((ai * 4 + m) * 2 + bj) * 1024) : (unsigned)((ai * HALF + m * 16) * 512 + bj * HALF) * 2u);
;                     const f32x4 v0 = acc[ai][bj][m][0], v1 = acc[ai][bj][m][1];
;                     u32x4 w; w.x = cvt_pk_bf16(actf<MODE>(v0[0]), actf<MODE>(v0[1])); w.y = cvt_pk_bf16(actf<MODE>(v0[2]), actf<MODE>(v0[3]));
;                     w.z = cvt_pk_bf16(actf<MODE>(v1[0]), actf<MODE>(v1[1])); w.w = cvt_pk_bf16(actf<MODE>(v1[2]), actf<MODE>(v1[3]));
;                     *(u32x4*)(base + off) = w; }
.LBB0_403:
	v_mul_f32_e32 v12, 0xbfb8aa3b, v12
	v_mul_f32_e32 v13, 0xbfb8aa3b, v13
	v_exp_f32_e32 v12, v12
	v_exp_f32_e32 v13, v13
	v_mul_f32_e32 v14, 0xbfb8aa3b, v14
	v_mul_f32_e32 v15, 0xbfb8aa3b, v15
	v_mul_f32_e32 v8, 0xbfb8aa3b, v8
	v_mul_f32_e32 v9, 0xbfb8aa3b, v9
	v_exp_f32_e32 v14, v14
	v_exp_f32_e32 v15, v15
	v_exp_f32_e32 v8, v8
	v_exp_f32_e32 v9, v9
	v_mul_f32_e32 v10, 0xbfb8aa3b, v10
	v_mul_f32_e32 v11, 0xbfb8aa3b, v11
	v_add_f32_e32 v12, 1.0, v12
	v_add_f32_e32 v13, 1.0, v13
	v_exp_f32_e32 v10, v10
	v_exp_f32_e32 v11, v11
	v_mul_f32_e32 v76, 0xbfb8aa3b, v76
	v_mul_f32_e32 v77, 0xbfb8aa3b, v77
	v_min_f32_e32 v12, 0x7149f2ca, v12
	v_min_f32_e32 v13, 0x7149f2ca, v13
	v_exp_f32_e32 v76, v76
	v_exp_f32_e32 v77, v77
	v_cvt_pk_bf16_f32 v12, v12, v13
	v_add_f32_e32 v13, 1.0, v14
	v_add_f32_e32 v14, 1.0, v15
	v_add_f32_e32 v8, 1.0, v8
	v_add_f32_e32 v9, 1.0, v9
	v_mul_f32_e32 v78, 0xbfb8aa3b, v78
	v_mul_f32_e32 v79, 0xbfb8aa3b, v79
	v_mul_f32_e32 v72, 0xbfb8aa3b, v72
	v_mul_f32_e32 v73, 0xbfb8aa3b, v73
	v_min_f32_e32 v13, 0x7149f2ca, v13
	v_min_f32_e32 v14, 0x7149f2ca, v14
	v_min_f32_e32 v8, 0x7149f2ca, v8
	v_min_f32_e32 v9, 0x7149f2ca, v9
	v_mov_b32_e32 v142, v212
	s_lshl_b32 s60, s72, 7
	v_exp_f32_e32 v78, v78
	v_exp_f32_e32 v79, v79
	v_exp_f32_e32 v72, v72
	v_exp_f32_e32 v73, v73
	v_cvt_pk_bf16_f32 v13, v13, v14
	v_cvt_pk_bf16_f32 v14, v8, v9
	v_add_f32_e32 v8, 1.0, v10
	v_add_f32_e32 v9, 1.0, v11
	s_add_i32 s60, s60, s54
	v_readfirstlane_b32 s55, v142
	v_mul_f32_e32 v74, 0xbfb8aa3b, v74
	v_mul_f32_e32 v75, 0xbfb8aa3b, v75
	v_min_f32_e32 v8, 0x7149f2ca, v8
	v_min_f32_e32 v9, 0x7149f2ca, v9
	s_ashr_i32 s55, s55, 6
	s_lshl_b32 s54, s60, 3
	v_add_f32_e32 v76, 1.0, v76
	v_add_f32_e32 v77, 1.0, v77
	v_exp_f32_e32 v74, v74
	v_exp_f32_e32 v75, v75
	v_cvt_pk_bf16_f32 v15, v8, v9
	v_mul_f32_e32 v8, 0xbfb8aa3b, v68
	v_mul_f32_e32 v9, 0xbfb8aa3b, v69
	s_nop 0
	v_min_f32_e32 v76, 0x7149f2ca, v76
	v_min_f32_e32 v77, 0x7149f2ca, v77
	v_exp_f32_e32 v8, v8
	v_exp_f32_e32 v9, v9
	s_addk_i32 s54, 0xd000
	v_cvt_pk_bf16_f32 v76, v76, v77
	v_add_f32_e32 v77, 1.0, v78
	v_add_f32_e32 v78, 1.0, v79
	v_add_f32_e32 v72, 1.0, v72
	v_add_f32_e32 v73, 1.0, v73
	v_mul_f32_e32 v10, 0xbfb8aa3b, v70
	v_mul_f32_e32 v11, 0xbfb8aa3b, v71
	s_ashr_i32 s55, s54, 31
	v_min_f32_e32 v77, 0x7149f2ca, v77
	v_min_f32_e32 v78, 0x7149f2ca, v78
	v_min_f32_e32 v72, 0x7149f2ca, v72
	v_min_f32_e32 v73, 0x7149f2ca, v73
	v_exp_f32_e32 v10, v10
	v_exp_f32_e32 v11, v11
	s_lshl_b64 s[54:55], s[54:55], 14
	v_lshlrev_b32_e32 v142, 4, v142
	v_cvt_pk_bf16_f32 v77, v77, v78
	v_cvt_pk_bf16_f32 v78, v72, v73
	v_add_f32_e32 v72, 1.0, v74
	v_add_f32_e32 v73, 1.0, v75
	s_add_u32 s54, s33, s54
	v_and_b32_e32 v142, 0x3f0, v142
	v_and_b32_e32 v190, 15, v212
	v_lshlrev_b32_e32 v190, 9, v190
	v_and_b32_e32 v191, 0xf0, v212
	v_or_b32_e32 v190, v190, v191
	v_and_b32_e32 v191, 0x100, v212
	v_lshlrev_b32_e32 v191, 7, v191
	v_or_b32_e32 v142, v190, v191
	v_min_f32_e32 v72, 0x7149f2ca, v72
	v_min_f32_e32 v73, 0x7149f2ca, v73
	v_add_f32_e32 v8, 1.0, v8
	v_add_f32_e32 v9, 1.0, v9
	s_addc_u32 s55, s37, s55
	v_cvt_pk_bf16_f32 v79, v72, v73
	v_add_u32_e32 v72, 0x16000, v142
	v_min_f32_e32 v8, 0x7149f2ca, v8
	v_min_f32_e32 v9, 0x7149f2ca, v9
	v_mul_f32_e32 v126, 0xbfb8aa3b, v126
	v_mul_f32_e32 v127, 0xbfb8aa3b, v127
	v_mul_f32_e32 v118, 0xbfb8aa3b, v118
	v_mul_f32_e32 v119, 0xbfb8aa3b, v119
	v_mul_f32_e32 v110, 0xbfb8aa3b, v110
	v_mul_f32_e32 v111, 0xbfb8aa3b, v111
	v_mul_f32_e32 v102, 0xbfb8aa3b, v102
	v_mul_f32_e32 v103, 0xbfb8aa3b, v103
	v_mul_f32_e32 v92, 0xbfb8aa3b, v92
	v_mul_f32_e32 v93, 0xbfb8aa3b, v93
	v_mul_f32_e32 v84, 0xbfb8aa3b, v84
	v_mul_f32_e32 v85, 0xbfb8aa3b, v85
	global_store_dwordx4 v72, v[12:15], s[54:55]
	v_cvt_pk_bf16_f32 v8, v8, v9
	v_add_f32_e32 v9, 1.0, v10
	v_add_f32_e32 v10, 1.0, v11
	v_mul_f32_e32 v11, 0xbfb8aa3b, v64
	v_mul_f32_e32 v13, 0xbfb8aa3b, v65
	v_exp_f32_e32 v126, v126
	v_exp_f32_e32 v127, v127
	v_exp_f32_e32 v118, v118
	v_exp_f32_e32 v119, v119
	v_exp_f32_e32 v110, v110
	v_exp_f32_e32 v111, v111
	v_exp_f32_e32 v102, v102
	v_exp_f32_e32 v103, v103
	v_exp_f32_e32 v92, v92
	v_exp_f32_e32 v93, v93
	v_exp_f32_e32 v84, v84
	v_exp_f32_e32 v85, v85
	v_exp_f32_e32 v11, v11
	v_exp_f32_e32 v13, v13
	v_mul_f32_e32 v128, 0xbfb8aa3b, v128
	v_mul_f32_e32 v129, 0xbfb8aa3b, v129
	v_mul_f32_e32 v122, 0xbfb8aa3b, v122
	v_mul_f32_e32 v123, 0xbfb8aa3b, v123
	v_mul_f32_e32 v120, 0xbfb8aa3b, v120
	v_mul_f32_e32 v121, 0xbfb8aa3b, v121
	v_mul_f32_e32 v114, 0xbfb8aa3b, v114
	v_mul_f32_e32 v115, 0xbfb8aa3b, v115
	v_mul_f32_e32 v112, 0xbfb8aa3b, v112
	v_mul_f32_e32 v113, 0xbfb8aa3b, v113
	v_mul_f32_e32 v106, 0xbfb8aa3b, v106
	v_mul_f32_e32 v107, 0xbfb8aa3b, v107
	v_mul_f32_e32 v104, 0xbfb8aa3b, v104
	v_mul_f32_e32 v105, 0xbfb8aa3b, v105
	v_mul_f32_e32 v98, 0xbfb8aa3b, v98
	v_mul_f32_e32 v99, 0xbfb8aa3b, v99
	v_mul_f32_e32 v94, 0xbfb8aa3b, v94
	v_mul_f32_e32 v95, 0xbfb8aa3b, v95
	v_mul_f32_e32 v88, 0xbfb8aa3b, v88
	v_mul_f32_e32 v89, 0xbfb8aa3b, v89
	v_mul_f32_e32 v86, 0xbfb8aa3b, v86
	v_mul_f32_e32 v87, 0xbfb8aa3b, v87
	v_mul_f32_e32 v80, 0xbfb8aa3b, v80
	v_mul_f32_e32 v81, 0xbfb8aa3b, v81
	v_exp_f32_e32 v128, v128
	v_exp_f32_e32 v129, v129
	v_exp_f32_e32 v122, v122
	v_exp_f32_e32 v123, v123
	v_exp_f32_e32 v120, v120
	v_exp_f32_e32 v121, v121
	v_exp_f32_e32 v114, v114
	v_exp_f32_e32 v115, v115
	v_exp_f32_e32 v112, v112
	v_exp_f32_e32 v113, v113
	v_exp_f32_e32 v106, v106
	v_exp_f32_e32 v107, v107
	v_exp_f32_e32 v104, v104
	v_exp_f32_e32 v105, v105
	v_exp_f32_e32 v98, v98
	v_exp_f32_e32 v99, v99
	v_exp_f32_e32 v94, v94
	v_exp_f32_e32 v95, v95
	v_exp_f32_e32 v88, v88
	v_exp_f32_e32 v89, v89
; __device__ __forceinline__ unsigned cvt_pk_bf16(float lo, float hi) { f32x2_t v = {lo, hi}; bf16x2_t b = __builtin_convertvector(v, bf16x2_t); return __builtin_bit_cast(unsigned, b); }
; template <int MODE> __device__ __forceinline__ float actf(float v) {
;     ...
;     if (MODE == 2) return fminf(1.0f + __builtin_amdgcn_exp2f(-LOG2E * v), 1e30f);
;     template <int MODE> __device__ __forceinline__ void run(const f32x4 (&acc)[2][2][4][2], const Unit& u, int wr, int wc, int fr, int fq) const {
;     ...
;         char* base = (MODE == 2) ? (char*)(O + (size_t)6 * ((size_t)MTOK * 512)) + ((size_t)(((pn - 12) * 128 + u.pm) * 8 + wid__)) * 16384
;                                  : (char*)(O + (size_t)t * ((size_t)MTOK * 512) + (size_t)u.pm * BM * 512 + (colt & 511));
;         unsigned off0 = (MODE == 2) ? (unsigned)((t__ & 63) * 16) : (unsigned)((wr * 64 + fr) * 512 + wc * 32 + 8 * fq) * 2u; asm volatile("" : "+v"(off0));
; #pragma unroll
;         for (int bj = 0; bj < 2; ++bj) {
; #pragma unroll
;             for (int ai = 0; ai < 2; ++ai)
; #pragma unroll
;                 for (int m = 0; m < 4; ++m) { const unsigned off = off0 + ((MODE == 2) ? (unsigned)(((ai * 4 + m) * 2 + bj) * 1024) : (unsigned)((ai * HALF + m * 16) * 512 + bj * HALF) * 2u);
;                     const f32x4 v0 = acc[ai][bj][m][0], v1 = acc[ai][bj][m][1];
;                     u32x4 w; w.x = cvt_pk_bf16(actf<MODE>(v0[0]), actf<MODE>(v0[1])); w.y = cvt_pk_bf16(actf<MODE>(v0[2]), actf<MODE>(v0[3]));
;                     w.z = cvt_pk_bf16(actf<MODE>(v1[0]), actf<MODE>(v1[1])); w.w = cvt_pk_bf16(actf<MODE>(v1[2]), actf<MODE>(v1[3]));
;                     *(u32x4*)(base + off) = w; }
	v_exp_f32_e32 v86, v86
	v_exp_f32_e32 v87, v87
	v_exp_f32_e32 v80, v80
	v_exp_f32_e32 v81, v81
	v_mul_f32_e32 v124, 0xbfb8aa3b, v124
	v_mul_f32_e32 v125, 0xbfb8aa3b, v125
	v_mul_f32_e32 v116, 0xbfb8aa3b, v116
	v_mul_f32_e32 v117, 0xbfb8aa3b, v117
	v_mul_f32_e32 v108, 0xbfb8aa3b, v108
	v_mul_f32_e32 v109, 0xbfb8aa3b, v109
	v_mul_f32_e32 v100, 0xbfb8aa3b, v100
	v_mul_f32_e32 v101, 0xbfb8aa3b, v101
	v_mul_f32_e32 v90, 0xbfb8aa3b, v90
	v_mul_f32_e32 v91, 0xbfb8aa3b, v91
	v_mul_f32_e32 v82, 0xbfb8aa3b, v82
	v_mul_f32_e32 v83, 0xbfb8aa3b, v83
	v_min_f32_e32 v9, 0x7149f2ca, v9
	v_min_f32_e32 v10, 0x7149f2ca, v10
	v_add_f32_e32 v126, 1.0, v126
	v_add_f32_e32 v127, 1.0, v127
	v_exp_f32_e32 v124, v124
	v_exp_f32_e32 v125, v125
	v_add_f32_e32 v118, 1.0, v118
	v_add_f32_e32 v119, 1.0, v119
	v_exp_f32_e32 v116, v116
	v_exp_f32_e32 v117, v117
	v_add_f32_e32 v110, 1.0, v110
	v_add_f32_e32 v111, 1.0, v111
	v_exp_f32_e32 v108, v108
	v_exp_f32_e32 v109, v109
	v_add_f32_e32 v102, 1.0, v102
	v_add_f32_e32 v103, 1.0, v103
	v_exp_f32_e32 v100, v100
	v_exp_f32_e32 v101, v101
	v_add_f32_e32 v92, 1.0, v92
	v_add_f32_e32 v93, 1.0, v93
	v_exp_f32_e32 v90, v90
	v_exp_f32_e32 v91, v91
	v_add_f32_e32 v84, 1.0, v84
	v_add_f32_e32 v85, 1.0, v85
	v_exp_f32_e32 v82, v82
	v_exp_f32_e32 v83, v83
	v_cvt_pk_bf16_f32 v9, v9, v10
	v_add_f32_e32 v10, 1.0, v11
	v_add_f32_e32 v11, 1.0, v13
	v_mul_f32_e32 v13, 0xbfb8aa3b, v66
	v_mul_f32_e32 v14, 0xbfb8aa3b, v67
	v_min_f32_e32 v126, 0x7149f2ca, v126
	v_min_f32_e32 v127, 0x7149f2ca, v127
	v_min_f32_e32 v118, 0x7149f2ca, v118
	v_min_f32_e32 v119, 0x7149f2ca, v119
	v_min_f32_e32 v110, 0x7149f2ca, v110
	v_min_f32_e32 v111, 0x7149f2ca, v111
	v_min_f32_e32 v102, 0x7149f2ca, v102
	v_min_f32_e32 v103, 0x7149f2ca, v103
	v_min_f32_e32 v92, 0x7149f2ca, v92
	v_min_f32_e32 v93, 0x7149f2ca, v93
	v_min_f32_e32 v84, 0x7149f2ca, v84
	v_min_f32_e32 v85, 0x7149f2ca, v85
	v_exp_f32_e32 v13, v13
	v_exp_f32_e32 v14, v14
	v_cvt_pk_bf16_f32 v126, v126, v127
	v_add_f32_e32 v127, 1.0, v128
	v_add_f32_e32 v128, 1.0, v129
	v_add_f32_e32 v122, 1.0, v122
	v_add_f32_e32 v123, 1.0, v123
	v_cvt_pk_bf16_f32 v118, v118, v119
	v_add_f32_e32 v119, 1.0, v120
	v_add_f32_e32 v120, 1.0, v121
	v_add_f32_e32 v114, 1.0, v114
	v_add_f32_e32 v115, 1.0, v115
	v_cvt_pk_bf16_f32 v110, v110, v111
	v_add_f32_e32 v111, 1.0, v112
	v_add_f32_e32 v112, 1.0, v113
	v_add_f32_e32 v106, 1.0, v106
	v_add_f32_e32 v107, 1.0, v107
	v_cvt_pk_bf16_f32 v102, v102, v103
	v_add_f32_e32 v103, 1.0, v104
	v_add_f32_e32 v104, 1.0, v105
	v_add_f32_e32 v98, 1.0, v98
	v_add_f32_e32 v99, 1.0, v99
	v_cvt_pk_bf16_f32 v92, v92, v93
	v_add_f32_e32 v93, 1.0, v94
	v_add_f32_e32 v94, 1.0, v95
	v_add_f32_e32 v88, 1.0, v88
	v_add_f32_e32 v89, 1.0, v89
	v_cvt_pk_bf16_f32 v84, v84, v85
	v_add_f32_e32 v85, 1.0, v86
	v_add_f32_e32 v86, 1.0, v87
	v_add_f32_e32 v80, 1.0, v80
	v_add_f32_e32 v81, 1.0, v81
	v_min_f32_e32 v127, 0x7149f2ca, v127
	v_min_f32_e32 v128, 0x7149f2ca, v128
	v_min_f32_e32 v122, 0x7149f2ca, v122
	v_min_f32_e32 v123, 0x7149f2ca, v123
	v_min_f32_e32 v119, 0x7149f2ca, v119
	v_min_f32_e32 v120, 0x7149f2ca, v120
	v_min_f32_e32 v114, 0x7149f2ca, v114
	v_min_f32_e32 v115, 0x7149f2ca, v115
	v_min_f32_e32 v111, 0x7149f2ca, v111
	v_min_f32_e32 v112, 0x7149f2ca, v112
	v_min_f32_e32 v106, 0x7149f2ca, v106
	v_min_f32_e32 v107, 0x7149f2ca, v107
	v_min_f32_e32 v103, 0x7149f2ca, v103
	v_min_f32_e32 v104, 0x7149f2ca, v104
	v_min_f32_e32 v98, 0x7149f2ca, v98
	v_min_f32_e32 v99, 0x7149f2ca, v99
	v_min_f32_e32 v93, 0x7149f2ca, v93
	v_min_f32_e32 v94, 0x7149f2ca, v94
	v_min_f32_e32 v88, 0x7149f2ca, v88
	v_min_f32_e32 v89, 0x7149f2ca, v89
	v_min_f32_e32 v85, 0x7149f2ca, v85
	v_min_f32_e32 v86, 0x7149f2ca, v86
	v_min_f32_e32 v80, 0x7149f2ca, v80
	v_min_f32_e32 v81, 0x7149f2ca, v81
	v_cvt_pk_bf16_f32 v127, v127, v128
	v_cvt_pk_bf16_f32 v128, v122, v123
	v_add_f32_e32 v122, 1.0, v124
	v_add_f32_e32 v123, 1.0, v125
	v_cvt_pk_bf16_f32 v119, v119, v120
	v_cvt_pk_bf16_f32 v120, v114, v115
	v_add_f32_e32 v114, 1.0, v116
	v_add_f32_e32 v115, 1.0, v117
	v_cvt_pk_bf16_f32 v111, v111, v112
	v_cvt_pk_bf16_f32 v112, v106, v107
	v_add_f32_e32 v106, 1.0, v108
	v_add_f32_e32 v107, 1.0, v109
	v_cvt_pk_bf16_f32 v103, v103, v104
	v_cvt_pk_bf16_f32 v104, v98, v99
	v_add_f32_e32 v98, 1.0, v100
	v_add_f32_e32 v99, 1.0, v101
	v_cvt_pk_bf16_f32 v93, v93, v94
	v_cvt_pk_bf16_f32 v94, v88, v89
	v_add_f32_e32 v88, 1.0, v90
	v_add_f32_e32 v89, 1.0, v91
	v_cvt_pk_bf16_f32 v85, v85, v86
	v_cvt_pk_bf16_f32 v86, v80, v81
	v_add_f32_e32 v80, 1.0, v82
	v_add_f32_e32 v81, 1.0, v83
	v_min_f32_e32 v10, 0x7149f2ca, v10
	v_min_f32_e32 v11, 0x7149f2ca, v11
	v_min_f32_e32 v122, 0x7149f2ca, v122
	v_min_f32_e32 v123, 0x7149f2ca, v123
	v_min_f32_e32 v114, 0x7149f2ca, v114
	v_min_f32_e32 v115, 0x7149f2ca, v115
	v_min_f32_e32 v106, 0x7149f2ca, v106
	v_min_f32_e32 v107, 0x7149f2ca, v107
	v_min_f32_e32 v98, 0x7149f2ca, v98
	v_min_f32_e32 v99, 0x7149f2ca, v99
	v_min_f32_e32 v88, 0x7149f2ca, v88
	v_min_f32_e32 v89, 0x7149f2ca, v89
	v_min_f32_e32 v80, 0x7149f2ca, v80
	v_min_f32_e32 v81, 0x7149f2ca, v81
	v_cvt_pk_bf16_f32 v10, v10, v11
	v_add_f32_e32 v11, 1.0, v13
	v_add_f32_e32 v13, 1.0, v14
	v_cvt_pk_bf16_f32 v129, v122, v123
	v_add_u32_e32 v122, 0x2000, v142
	v_cvt_pk_bf16_f32 v121, v114, v115
	v_add_u32_e32 v114, 0x4000, v142
	v_cvt_pk_bf16_f32 v113, v106, v107
	v_add_u32_e32 v106, 0x6000, v142
	v_cvt_pk_bf16_f32 v105, v98, v99
	v_add_u32_e32 v98, 0x10000, v142
	v_cvt_pk_bf16_f32 v95, v88, v89
	v_add_u32_e32 v88, 0x12000, v142
	v_cvt_pk_bf16_f32 v87, v80, v81
	v_add_u32_e32 v80, 0x14000, v142
	v_min_f32_e32 v11, 0x7149f2ca, v11
	v_min_f32_e32 v13, 0x7149f2ca, v13
; __device__ __forceinline__ unsigned cvt_pk_bf16(float lo, float hi) { f32x2_t v = {lo, hi}; bf16x2_t b = __builtin_convertvector(v, bf16x2_t); return __builtin_bit_cast(unsigned, b); }
; template <int MODE> __device__ __forceinline__ float actf(float v) {
;     ...
;     if (MODE == 2) return fminf(1.0f + __builtin_amdgcn_exp2f(-LOG2E * v), 1e30f);
;     template <int MODE> __device__ __forceinline__ void run(const f32x4 (&acc)[2][2][4][2], const Unit& u, int wr, int wc, int fr, int fq) const {
;     ...
;         char* base = (MODE == 2) ? (char*)(O + (size_t)6 * ((size_t)MTOK * 512)) + ((size_t)(((pn - 12) * 128 + u.pm) * 8 + wid__)) * 16384
;                                  : (char*)(O + (size_t)t * ((size_t)MTOK * 512) + (size_t)u.pm * BM * 512 + (colt & 511));
;         unsigned off0 = (MODE == 2) ? (unsigned)((t__ & 63) * 16) : (unsigned)((wr * 64 + fr) * 512 + wc * 32 + 8 * fq) * 2u; asm volatile("" : "+v"(off0));
; #pragma unroll
;         for (int bj = 0; bj < 2; ++bj) {
; #pragma unroll
;             for (int ai = 0; ai < 2; ++ai)
; #pragma unroll
;                 for (int m = 0; m < 4; ++m) { const unsigned off = off0 + ((MODE == 2) ? (unsigned)(((ai * 4 + m) * 2 + bj) * 1024) : (unsigned)((ai * HALF + m * 16) * 512 + bj * HALF) * 2u);
;                     const f32x4 v0 = acc[ai][bj][m][0], v1 = acc[ai][bj][m][1];
;                     u32x4 w; w.x = cvt_pk_bf16(actf<MODE>(v0[0]), actf<MODE>(v0[1])); w.y = cvt_pk_bf16(actf<MODE>(v0[2]), actf<MODE>(v0[3]));
;                     w.z = cvt_pk_bf16(actf<MODE>(v1[0]), actf<MODE>(v1[1])); w.w = cvt_pk_bf16(actf<MODE>(v1[2]), actf<MODE>(v1[3]));
;                     *(u32x4*)(base + off) = w; }
	global_store_dwordx4 v142, v[126:129], s[54:55]
	global_store_dwordx4 v122, v[118:121], s[54:55]
	global_store_dwordx4 v114, v[110:113], s[54:55]
	global_store_dwordx4 v106, v[102:105], s[54:55]
	global_store_dwordx4 v98, v[92:95], s[54:55]
	global_store_dwordx4 v88, v[84:87], s[54:55]
	global_store_dwordx4 v80, v[76:79], s[54:55]
	v_add_u32_e32 v12, 0x100, v142
	v_cvt_pk_bf16_f32 v11, v11, v13
	global_store_dwordx4 v12, v[8:11], s[54:55]
	v_mul_f32_e32 v13, 0xbfb8aa3b, v57
	v_exp_f32_e32 v13, v13
	v_mul_f32_e32 v8, 0xbfb8aa3b, v60
	v_mul_f32_e32 v9, 0xbfb8aa3b, v61
	v_exp_f32_e32 v8, v8
	v_exp_f32_e32 v9, v9
	v_mul_f32_e32 v10, 0xbfb8aa3b, v62
	v_mul_f32_e32 v11, 0xbfb8aa3b, v63
	v_exp_f32_e32 v10, v10
	v_exp_f32_e32 v11, v11
	v_add_f32_e32 v8, 1.0, v8
	v_add_f32_e32 v9, 1.0, v9
	v_min_f32_e32 v8, 0x7149f2ca, v8
	v_min_f32_e32 v9, 0x7149f2ca, v9
	v_cvt_pk_bf16_f32 v8, v8, v9
	v_add_f32_e32 v9, 1.0, v10
	v_add_f32_e32 v10, 1.0, v11
	v_mul_f32_e32 v11, 0xbfb8aa3b, v56
	v_exp_f32_e32 v11, v11
	v_min_f32_e32 v9, 0x7149f2ca, v9
	v_min_f32_e32 v10, 0x7149f2ca, v10
	v_cvt_pk_bf16_f32 v9, v9, v10
	v_add_f32_e32 v10, 1.0, v11
	v_add_f32_e32 v11, 1.0, v13
	v_mul_f32_e32 v13, 0xbfb8aa3b, v58
	v_mul_f32_e32 v14, 0xbfb8aa3b, v59
	v_exp_f32_e32 v13, v13
	v_exp_f32_e32 v14, v14
	v_min_f32_e32 v10, 0x7149f2ca, v10
	v_min_f32_e32 v11, 0x7149f2ca, v11
	v_cvt_pk_bf16_f32 v10, v10, v11
	v_add_f32_e32 v11, 1.0, v13
	v_add_f32_e32 v13, 1.0, v14
	v_min_f32_e32 v11, 0x7149f2ca, v11
	v_min_f32_e32 v13, 0x7149f2ca, v13
	v_add_u32_e32 v12, 0x2100, v142
	v_cvt_pk_bf16_f32 v11, v11, v13
	global_store_dwordx4 v12, v[8:11], s[54:55]
	v_mul_f32_e32 v13, 0xbfb8aa3b, v49
	v_exp_f32_e32 v13, v13
	v_mul_f32_e32 v8, 0xbfb8aa3b, v52
	v_mul_f32_e32 v9, 0xbfb8aa3b, v53
	v_exp_f32_e32 v8, v8
	v_exp_f32_e32 v9, v9
	v_mul_f32_e32 v10, 0xbfb8aa3b, v54
	v_mul_f32_e32 v11, 0xbfb8aa3b, v55
	v_exp_f32_e32 v10, v10
	v_exp_f32_e32 v11, v11
	v_add_f32_e32 v8, 1.0, v8
	v_add_f32_e32 v9, 1.0, v9
	v_min_f32_e32 v8, 0x7149f2ca, v8
	v_min_f32_e32 v9, 0x7149f2ca, v9
	v_cvt_pk_bf16_f32 v8, v8, v9
	v_add_f32_e32 v9, 1.0, v10
	v_add_f32_e32 v10, 1.0, v11
	v_mul_f32_e32 v11, 0xbfb8aa3b, v48
	v_exp_f32_e32 v11, v11
	v_min_f32_e32 v9, 0x7149f2ca, v9
	v_min_f32_e32 v10, 0x7149f2ca, v10
	v_cvt_pk_bf16_f32 v9, v9, v10
	v_add_f32_e32 v10, 1.0, v11
	v_add_f32_e32 v11, 1.0, v13
	v_mul_f32_e32 v13, 0xbfb8aa3b, v50
	v_mul_f32_e32 v14, 0xbfb8aa3b, v51
	v_exp_f32_e32 v13, v13
	v_exp_f32_e32 v14, v14
	v_min_f32_e32 v10, 0x7149f2ca, v10
	v_min_f32_e32 v11, 0x7149f2ca, v11
	v_cvt_pk_bf16_f32 v10, v10, v11
	v_add_f32_e32 v11, 1.0, v13
	v_add_f32_e32 v13, 1.0, v14
	v_min_f32_e32 v11, 0x7149f2ca, v11
	v_min_f32_e32 v13, 0x7149f2ca, v13
	v_add_u32_e32 v12, 0x4100, v142
	v_cvt_pk_bf16_f32 v11, v11, v13
	global_store_dwordx4 v12, v[8:11], s[54:55]
	v_mul_f32_e32 v13, 0xbfb8aa3b, v41
	v_exp_f32_e32 v13, v13
	v_mul_f32_e32 v8, 0xbfb8aa3b, v44
	v_mul_f32_e32 v9, 0xbfb8aa3b, v45
	v_exp_f32_e32 v8, v8
	v_exp_f32_e32 v9, v9
	v_mul_f32_e32 v10, 0xbfb8aa3b, v46
	v_mul_f32_e32 v11, 0xbfb8aa3b, v47
	v_exp_f32_e32 v10, v10
	v_exp_f32_e32 v11, v11
	v_add_f32_e32 v8, 1.0, v8
	v_add_f32_e32 v9, 1.0, v9
	v_min_f32_e32 v8, 0x7149f2ca, v8
	v_min_f32_e32 v9, 0x7149f2ca, v9
	v_cvt_pk_bf16_f32 v8, v8, v9
	v_add_f32_e32 v9, 1.0, v10
	v_add_f32_e32 v10, 1.0, v11
	v_mul_f32_e32 v11, 0xbfb8aa3b, v40
	v_exp_f32_e32 v11, v11
	v_min_f32_e32 v9, 0x7149f2ca, v9
	v_min_f32_e32 v10, 0x7149f2ca, v10
	v_cvt_pk_bf16_f32 v9, v9, v10
	v_add_f32_e32 v10, 1.0, v11
	v_add_f32_e32 v11, 1.0, v13
	v_mul_f32_e32 v13, 0xbfb8aa3b, v42
	v_mul_f32_e32 v14, 0xbfb8aa3b, v43
	v_exp_f32_e32 v13, v13
	v_exp_f32_e32 v14, v14
	v_min_f32_e32 v10, 0x7149f2ca, v10
	v_min_f32_e32 v11, 0x7149f2ca, v11
	v_cvt_pk_bf16_f32 v10, v10, v11
	v_add_f32_e32 v11, 1.0, v13
	v_add_f32_e32 v13, 1.0, v14
	v_min_f32_e32 v11, 0x7149f2ca, v11
	v_min_f32_e32 v13, 0x7149f2ca, v13
	v_add_u32_e32 v12, 0x6100, v142
	v_cvt_pk_bf16_f32 v11, v11, v13
	global_store_dwordx4 v12, v[8:11], s[54:55]
	v_mul_f32_e32 v13, 0xbfb8aa3b, v33
	v_exp_f32_e32 v13, v13
	v_mul_f32_e32 v8, 0xbfb8aa3b, v36
	v_mul_f32_e32 v9, 0xbfb8aa3b, v37
	v_exp_f32_e32 v8, v8
	v_exp_f32_e32 v9, v9
	v_mul_f32_e32 v10, 0xbfb8aa3b, v38
	v_mul_f32_e32 v11, 0xbfb8aa3b, v39
	v_exp_f32_e32 v10, v10
	v_exp_f32_e32 v11, v11
	v_add_f32_e32 v8, 1.0, v8
	v_add_f32_e32 v9, 1.0, v9
; __device__ __forceinline__ unsigned cvt_pk_bf16(float lo, float hi) { f32x2_t v = {lo, hi}; bf16x2_t b = __builtin_convertvector(v, bf16x2_t); return __builtin_bit_cast(unsigned, b); }
; template <int MODE> __device__ __forceinline__ float actf(float v) {
;     ...
;     if (MODE == 2) return fminf(1.0f + __builtin_amdgcn_exp2f(-LOG2E * v), 1e30f);
;     template <int MODE> __device__ __forceinline__ void run(const f32x4 (&acc)[2][2][4][2], const Unit& u, int wr, int wc, int fr, int fq) const {
;     ...
;         char* base = (MODE == 2) ? (char*)(O + (size_t)6 * ((size_t)MTOK * 512)) + ((size_t)(((pn - 12) * 128 + u.pm) * 8 + wid__)) * 16384
;                                  : (char*)(O + (size_t)t * ((size_t)MTOK * 512) + (size_t)u.pm * BM * 512 + (colt & 511));
;         unsigned off0 = (MODE == 2) ? (unsigned)((t__ & 63) * 16) : (unsigned)((wr * 64 + fr) * 512 + wc * 32 + 8 * fq) * 2u; asm volatile("" : "+v"(off0));
; #pragma unroll
;         for (int bj = 0; bj < 2; ++bj) {
; #pragma unroll
;             for (int ai = 0; ai < 2; ++ai)
; #pragma unroll
;                 for (int m = 0; m < 4; ++m) { const unsigned off = off0 + ((MODE == 2) ? (unsigned)(((ai * 4 + m) * 2 + bj) * 1024) : (unsigned)((ai * HALF + m * 16) * 512 + bj * HALF) * 2u);
;                     const f32x4 v0 = acc[ai][bj][m][0], v1 = acc[ai][bj][m][1];
;                     u32x4 w; w.x = cvt_pk_bf16(actf<MODE>(v0[0]), actf<MODE>(v0[1])); w.y = cvt_pk_bf16(actf<MODE>(v0[2]), actf<MODE>(v0[3]));
;                     w.z = cvt_pk_bf16(actf<MODE>(v1[0]), actf<MODE>(v1[1])); w.w = cvt_pk_bf16(actf<MODE>(v1[2]), actf<MODE>(v1[3]));
;                     *(u32x4*)(base + off) = w; }
	v_min_f32_e32 v8, 0x7149f2ca, v8
	v_min_f32_e32 v9, 0x7149f2ca, v9
	v_cvt_pk_bf16_f32 v8, v8, v9
	v_add_f32_e32 v9, 1.0, v10
	v_add_f32_e32 v10, 1.0, v11
	v_mul_f32_e32 v11, 0xbfb8aa3b, v32
	v_exp_f32_e32 v11, v11
	v_min_f32_e32 v9, 0x7149f2ca, v9
	v_min_f32_e32 v10, 0x7149f2ca, v10
	v_cvt_pk_bf16_f32 v9, v9, v10
	v_add_f32_e32 v10, 1.0, v11
	v_add_f32_e32 v11, 1.0, v13
	v_mul_f32_e32 v13, 0xbfb8aa3b, v34
	v_mul_f32_e32 v14, 0xbfb8aa3b, v35
	v_exp_f32_e32 v13, v13
	v_exp_f32_e32 v14, v14
	v_min_f32_e32 v10, 0x7149f2ca, v10
	v_min_f32_e32 v11, 0x7149f2ca, v11
	v_cvt_pk_bf16_f32 v10, v10, v11
	v_add_f32_e32 v11, 1.0, v13
	v_add_f32_e32 v13, 1.0, v14
	v_min_f32_e32 v11, 0x7149f2ca, v11
	v_min_f32_e32 v13, 0x7149f2ca, v13
	v_add_u32_e32 v12, 0x10100, v142
	v_cvt_pk_bf16_f32 v11, v11, v13
	global_store_dwordx4 v12, v[8:11], s[54:55]
	v_mul_f32_e32 v13, 0xbfb8aa3b, v25
	v_exp_f32_e32 v13, v13
	v_mul_f32_e32 v8, 0xbfb8aa3b, v28
	v_mul_f32_e32 v9, 0xbfb8aa3b, v29
	v_exp_f32_e32 v8, v8
	v_exp_f32_e32 v9, v9
	v_mul_f32_e32 v10, 0xbfb8aa3b, v30
	v_mul_f32_e32 v11, 0xbfb8aa3b, v31
	v_exp_f32_e32 v10, v10
	v_exp_f32_e32 v11, v11
	v_add_f32_e32 v8, 1.0, v8
	v_add_f32_e32 v9, 1.0, v9
	v_min_f32_e32 v8, 0x7149f2ca, v8
	v_min_f32_e32 v9, 0x7149f2ca, v9
	v_cvt_pk_bf16_f32 v8, v8, v9
	v_add_f32_e32 v9, 1.0, v10
	v_add_f32_e32 v10, 1.0, v11
	v_mul_f32_e32 v11, 0xbfb8aa3b, v24
	v_exp_f32_e32 v11, v11
	v_min_f32_e32 v9, 0x7149f2ca, v9
	v_min_f32_e32 v10, 0x7149f2ca, v10
	v_cvt_pk_bf16_f32 v9, v9, v10
	v_add_f32_e32 v10, 1.0, v11
	v_add_f32_e32 v11, 1.0, v13
	v_mul_f32_e32 v13, 0xbfb8aa3b, v26
	v_mul_f32_e32 v14, 0xbfb8aa3b, v27
	v_exp_f32_e32 v13, v13
	v_exp_f32_e32 v14, v14
	v_min_f32_e32 v10, 0x7149f2ca, v10
	v_min_f32_e32 v11, 0x7149f2ca, v11
	v_cvt_pk_bf16_f32 v10, v10, v11
	v_add_f32_e32 v11, 1.0, v13
	v_add_f32_e32 v13, 1.0, v14
	v_min_f32_e32 v11, 0x7149f2ca, v11
	v_min_f32_e32 v13, 0x7149f2ca, v13
	v_add_u32_e32 v12, 0x12100, v142
	v_cvt_pk_bf16_f32 v11, v11, v13
	global_store_dwordx4 v12, v[8:11], s[54:55]
	v_mul_f32_e32 v13, 0xbfb8aa3b, v17
	v_exp_f32_e32 v13, v13
	v_mul_f32_e32 v8, 0xbfb8aa3b, v20
	v_mul_f32_e32 v9, 0xbfb8aa3b, v21
	v_exp_f32_e32 v8, v8
	v_exp_f32_e32 v9, v9
	v_mul_f32_e32 v10, 0xbfb8aa3b, v22
	v_mul_f32_e32 v11, 0xbfb8aa3b, v23
	v_exp_f32_e32 v10, v10
	v_exp_f32_e32 v11, v11
	v_add_f32_e32 v8, 1.0, v8
	v_add_f32_e32 v9, 1.0, v9
	v_min_f32_e32 v8, 0x7149f2ca, v8
	v_min_f32_e32 v9, 0x7149f2ca, v9
	v_cvt_pk_bf16_f32 v8, v8, v9
	v_add_f32_e32 v9, 1.0, v10
	v_add_f32_e32 v10, 1.0, v11
	v_mul_f32_e32 v11, 0xbfb8aa3b, v16
	v_exp_f32_e32 v11, v11
	v_mul_f32_e32 v4, 0xbfb8aa3b, v4
	v_mul_f32_e32 v5, 0xbfb8aa3b, v5
	v_exp_f32_e32 v4, v4
	v_exp_f32_e32 v5, v5
	v_min_f32_e32 v9, 0x7149f2ca, v9
	v_min_f32_e32 v10, 0x7149f2ca, v10
	v_mul_f32_e32 v6, 0xbfb8aa3b, v6
	v_mul_f32_e32 v7, 0xbfb8aa3b, v7
	v_mul_f32_e32 v0, 0xbfb8aa3b, v0
	v_mul_f32_e32 v1, 0xbfb8aa3b, v1
	v_cvt_pk_bf16_f32 v9, v9, v10
	v_add_f32_e32 v10, 1.0, v11
	v_add_f32_e32 v11, 1.0, v13
	v_mul_f32_e32 v13, 0xbfb8aa3b, v18
	v_mul_f32_e32 v14, 0xbfb8aa3b, v19
	v_exp_f32_e32 v6, v6
	v_exp_f32_e32 v7, v7
	v_exp_f32_e32 v0, v0
	v_exp_f32_e32 v1, v1
	v_exp_f32_e32 v13, v13
	v_exp_f32_e32 v14, v14
	v_mul_f32_e32 v2, 0xbfb8aa3b, v2
	v_mul_f32_e32 v3, 0xbfb8aa3b, v3
	v_add_f32_e32 v4, 1.0, v4
	v_add_f32_e32 v5, 1.0, v5
	v_exp_f32_e32 v2, v2
	v_exp_f32_e32 v3, v3
	v_min_f32_e32 v4, 0x7149f2ca, v4
	v_min_f32_e32 v5, 0x7149f2ca, v5
	v_min_f32_e32 v10, 0x7149f2ca, v10
	v_min_f32_e32 v11, 0x7149f2ca, v11
	v_cvt_pk_bf16_f32 v4, v4, v5
	v_add_f32_e32 v5, 1.0, v6
	v_add_f32_e32 v6, 1.0, v7
	v_add_f32_e32 v0, 1.0, v0
	v_add_f32_e32 v1, 1.0, v1
	v_cvt_pk_bf16_f32 v10, v10, v11
	v_add_f32_e32 v11, 1.0, v13
	v_add_f32_e32 v13, 1.0, v14
	v_min_f32_e32 v5, 0x7149f2ca, v5
	v_min_f32_e32 v6, 0x7149f2ca, v6
	v_min_f32_e32 v0, 0x7149f2ca, v0
	v_min_f32_e32 v1, 0x7149f2ca, v1
	v_min_f32_e32 v11, 0x7149f2ca, v11
	v_min_f32_e32 v13, 0x7149f2ca, v13
	v_cvt_pk_bf16_f32 v5, v5, v6
	v_cvt_pk_bf16_f32 v6, v0, v1
	v_add_f32_e32 v0, 1.0, v2
	v_add_f32_e32 v1, 1.0, v3
	v_add_u32_e32 v12, 0x14100, v142
	v_cvt_pk_bf16_f32 v11, v11, v13
	v_min_f32_e32 v0, 0x7149f2ca, v0
	v_min_f32_e32 v1, 0x7149f2ca, v1
	global_store_dwordx4 v12, v[8:11], s[54:55]
	v_cvt_pk_bf16_f32 v7, v0, v1
	s_nop 0
	v_add_u32_e32 v8, 0x16100, v142
	global_store_dwordx4 v8, v[4:7], s[54:55]
